# GEMM compute segments: removed the no-op s_setprio 0 / s_setprio 1 pair between MFMA 16 and 17 (A/B of mid-segment flips)
# speedup vs baseline: 1.0018x; 1.0018x over previous
; #define PG8_STAGE(bufoff, gbase, voff) do { _Pragma("unroll") for (int _i = 0; _i < 2; ++_i) \
;         __builtin_amdgcn_global_load_lds((const unsigned*)((const char*)(gbase) + (voff)[_i]), (PG8_LAS unsigned*)(lds + (bufoff) + ldsw + _i * 8192), 16, 0, 0); } while (0)
; #define PG8_LDA(dst, b, h) do { _Pragma("unroll") for (int m = 0; m < 4; ++m) _Pragma("unroll") for (int k = 0; k < 2; ++k) dst[m][k] = *(const PG8_LAS bf16x8*)(lds + PG8_SA(b, h) + aoff + m * 2048 + k * 1024); } while (0)
; #define PG8_LDB(dst, b, h) do { _Pragma("unroll") for (int n = 0; n < 2; ++n) _Pragma("unroll") for (int k = 0; k < 2; ++k) dst[n][k] = *(const PG8_LAS bf16x8*)(lds + PG8_SB(b, h) + boff + n * 2048 + k * 1024); } while (0)
; #define PG8_MMA(ai, bj, At, Bt) do { __builtin_amdgcn_s_setprio(1); _Pragma("unroll") for (int m = 0; m < 4; ++m) _Pragma("unroll") for (int n = 0; n < 2; ++n) _Pragma("unroll") for (int k = 0; k < 2; ++k) \
;         acc[ai][bj][m][n] = __builtin_amdgcn_mfma_f32_16x16x32_bf16(Bt[n][k], At[m][k], acc[ai][bj][m][n], 0, 0, 0); __builtin_amdgcn_s_setprio(0); } while (0)
; #define PG8_WAIT_V(n) asm volatile("s_waitcnt vmcnt(" #n ")" ::: "memory")
; #define PG8_WAIT_L(n) asm volatile("s_waitcnt lgkmcnt(" #n ")" ::: "memory")
; #define PG8_BAR __builtin_amdgcn_s_barrier()
; #define PG8_SCHED __builtin_amdgcn_sched_barrier(0)
; template <class Epi, class Sched, bool ALIGN_EPI = false, bool SP2 = false>
; __device__ __forceinline__ void gemm_phase(PG8_LAS unsigned char* lds, const Gemm g, const Sched& S, const Epi& E) {
;     ...
;             PG8_LDB(B0, 0, 0); PG8_LDB(B1, 0, 1); PG8_SCHED; PG8_LDA(At, 0, 0); PG8_STAGE(PG8_SA(1, 1), a1 + hstep, voffA);
;             PG8_WAIT_V(8); PG8_WAIT_L(0); PG8_BAR; PG8_MMA(0, 0, At, B0); PG8_MMA(0, 1, At, B1); PG8_BAR; PG8_SCHED;
;             PG8_LDA(At, 0, 1); PG8_STAGE(PG8_SB(0, 0), b2, voffB); PG8_STAGE(PG8_SB(0, 1), b2 + hstep, voffB); PG8_STAGE(PG8_SA(0, 0), a2, voffA);
;             PG8_WAIT_V(8); PG8_WAIT_L(0); PG8_BAR; PG8_MMA(1, 0, At, B0); PG8_MMA(1, 1, At, B1); PG8_BAR; PG8_SCHED;
.LBB0_25:
	s_add_i32 s88, 0, 0x10000
	s_add_i32 s90, 0, 0x14000
	ds_read_b128 v[142:145], v200
	ds_read_b128 v[146:149], v200 offset:1024
	ds_read_b128 v[150:153], v200 offset:2048
	ds_read_b128 v[154:157], v200 offset:3072
	ds_read_b128 v[164:167], v200 offset:16384
	ds_read_b128 v[168:171], v200 offset:17408
	ds_read_b128 v[172:175], v200 offset:18432
	ds_read_b128 v[176:179], v200 offset:19456
	s_add_i32 m0, s29, 0xc000
	ds_read_b128 v[180:183], v141
	ds_read_b128 v[184:187], v141 offset:1024
	ds_read_b128 v[188:191], v141 offset:2048
	ds_read_b128 v[192:195], v141 offset:3072
	ds_read_b128 v[196:199], v141 offset:4096
	ds_read_b128 v[222:225], v141 offset:5120
	ds_read_b128 v[226:229], v141 offset:6144
	ds_read_b128 v[230:233], v141 offset:7168
	global_load_lds_dwordx4 v134, s[80:81]
	s_add_i32 m0, s29, 0xe000
	s_nop 0
	global_load_lds_dwordx4 v136, s[80:81]
	s_add_u32 s4, s80, 0xfff80080
	s_addc_u32 s5, s81, -1
	s_cmp_eq_u32 s87, 28
	s_cselect_b32 s53, s55, s5
	s_cselect_b32 s52, s83, s4
	s_cselect_b32 s5, s73, s86
	s_cselect_b32 s4, s84, s85
	s_waitcnt vmcnt(8)
	s_waitcnt lgkmcnt(0)
	s_barrier
	s_setprio 1
	s_waitcnt lgkmcnt(0)
	v_mfma_f32_16x16x32_bf16 v[124:127], v[142:145], v[180:183], v[124:127]
	v_mfma_f32_16x16x32_bf16 v[120:123], v[150:153], v[180:183], v[120:123]
	v_mfma_f32_16x16x32_bf16 v[116:119], v[142:145], v[188:191], v[116:119]
	v_mfma_f32_16x16x32_bf16 v[112:115], v[150:153], v[188:191], v[112:115]
	v_mfma_f32_16x16x32_bf16 v[100:103], v[142:145], v[196:199], v[100:103]
	v_mfma_f32_16x16x32_bf16 v[96:99], v[150:153], v[196:199], v[96:99]
	v_mfma_f32_16x16x32_bf16 v[84:87], v[142:145], v[226:229], v[84:87]
	v_mfma_f32_16x16x32_bf16 v[80:83], v[150:153], v[226:229], v[80:83]
	v_mfma_f32_16x16x32_bf16 v[124:127], v[146:149], v[184:187], v[124:127]
	v_mfma_f32_16x16x32_bf16 v[120:123], v[154:157], v[184:187], v[120:123]
	v_mfma_f32_16x16x32_bf16 v[116:119], v[146:149], v[192:195], v[116:119]
	v_mfma_f32_16x16x32_bf16 v[112:115], v[154:157], v[192:195], v[112:115]
	v_mfma_f32_16x16x32_bf16 v[100:103], v[146:149], v[222:225], v[100:103]
	v_mfma_f32_16x16x32_bf16 v[96:99], v[154:157], v[222:225], v[96:99]
	v_mfma_f32_16x16x32_bf16 v[84:87], v[146:149], v[230:233], v[84:87]
	v_mfma_f32_16x16x32_bf16 v[80:83], v[154:157], v[230:233], v[80:83]
	v_mfma_f32_16x16x32_bf16 v[108:111], v[164:167], v[180:183], v[108:111]
	v_mfma_f32_16x16x32_bf16 v[104:107], v[172:175], v[180:183], v[104:107]
	v_mfma_f32_16x16x32_bf16 v[92:95], v[164:167], v[188:191], v[92:95]
	v_mfma_f32_16x16x32_bf16 v[88:91], v[172:175], v[188:191], v[88:91]
	v_mfma_f32_16x16x32_bf16 v[76:79], v[164:167], v[196:199], v[76:79]
	v_mfma_f32_16x16x32_bf16 v[72:75], v[172:175], v[196:199], v[72:75]
	v_mfma_f32_16x16x32_bf16 v[68:71], v[164:167], v[226:229], v[68:71]
	v_mfma_f32_16x16x32_bf16 v[64:67], v[172:175], v[226:229], v[64:67]
	v_mfma_f32_16x16x32_bf16 v[108:111], v[168:171], v[184:187], v[108:111]
	v_mfma_f32_16x16x32_bf16 v[104:107], v[176:179], v[184:187], v[104:107]
	v_mfma_f32_16x16x32_bf16 v[92:95], v[168:171], v[192:195], v[92:95]
	v_mfma_f32_16x16x32_bf16 v[88:91], v[176:179], v[192:195], v[88:91]
	v_mfma_f32_16x16x32_bf16 v[76:79], v[168:171], v[222:225], v[76:79]
	v_mfma_f32_16x16x32_bf16 v[72:75], v[176:179], v[222:225], v[72:75]
	v_mfma_f32_16x16x32_bf16 v[68:71], v[168:171], v[230:233], v[68:71]
	v_mfma_f32_16x16x32_bf16 v[64:67], v[176:179], v[230:233], v[64:67]
	s_setprio 0
	s_barrier
	s_add_i32 s88, s88, s28
	s_mov_b32 m0, s88
	ds_read_b128 v[180:183], v141 offset:16384
	ds_read_b128 v[184:187], v141 offset:17408
	ds_read_b128 v[188:191], v141 offset:18432
	ds_read_b128 v[192:195], v141 offset:19456
	ds_read_b128 v[196:199], v141 offset:20480
	ds_read_b128 v[222:225], v141 offset:21504
	ds_read_b128 v[226:229], v141 offset:22528
	ds_read_b128 v[230:233], v141 offset:23552
	global_load_lds_dwordx4 v160, s[4:5]
	s_add_i32 m0, s88, 0x2000
	s_add_u32 s88, s4, 0x80000
	s_addc_u32 s89, s5, 0
	s_add_i32 s90, s90, s28
	global_load_lds_dwordx4 v128, s[4:5]
	s_mov_b32 m0, s90
	s_nop 0
	global_load_lds_dwordx4 v160, s[88:89]
	s_add_i32 m0, s90, 0x2000
	s_nop 0
	global_load_lds_dwordx4 v128, s[88:89]
	s_mov_b32 m0, s29
	s_nop 0
	global_load_lds_dwordx4 v132, s[52:53]
	s_mov_b32 m0, s45
	s_nop 0
	global_load_lds_dwordx4 v130, s[52:53]
	s_add_u32 s98, s52, 0x80
	s_addc_u32 s99, s53, 0
	s_waitcnt vmcnt(8)
	s_waitcnt lgkmcnt(0)
	s_barrier
	s_setprio 1
	s_waitcnt lgkmcnt(0)
	v_mfma_f32_16x16x32_bf16 v[60:63], v[142:145], v[180:183], v[60:63]
	v_mfma_f32_16x16x32_bf16 v[56:59], v[150:153], v[180:183], v[56:59]
	v_mfma_f32_16x16x32_bf16 v[52:55], v[142:145], v[188:191], v[52:55]
	v_mfma_f32_16x16x32_bf16 v[48:51], v[150:153], v[188:191], v[48:51]
	v_mfma_f32_16x16x32_bf16 v[36:39], v[142:145], v[196:199], v[36:39]
	v_mfma_f32_16x16x32_bf16 v[32:35], v[150:153], v[196:199], v[32:35]
	v_mfma_f32_16x16x32_bf16 v[20:23], v[142:145], v[226:229], v[20:23]
	v_mfma_f32_16x16x32_bf16 v[16:19], v[150:153], v[226:229], v[16:19]
	v_mfma_f32_16x16x32_bf16 v[60:63], v[146:149], v[184:187], v[60:63]
	v_mfma_f32_16x16x32_bf16 v[56:59], v[154:157], v[184:187], v[56:59]
	v_mfma_f32_16x16x32_bf16 v[52:55], v[146:149], v[192:195], v[52:55]
	v_mfma_f32_16x16x32_bf16 v[48:51], v[154:157], v[192:195], v[48:51]
	v_mfma_f32_16x16x32_bf16 v[36:39], v[146:149], v[222:225], v[36:39]
	v_mfma_f32_16x16x32_bf16 v[32:35], v[154:157], v[222:225], v[32:35]
	v_mfma_f32_16x16x32_bf16 v[20:23], v[146:149], v[230:233], v[20:23]
	v_mfma_f32_16x16x32_bf16 v[16:19], v[154:157], v[230:233], v[16:19]
	v_mfma_f32_16x16x32_bf16 v[44:47], v[164:167], v[180:183], v[44:47]
	v_mfma_f32_16x16x32_bf16 v[40:43], v[172:175], v[180:183], v[40:43]
	v_mfma_f32_16x16x32_bf16 v[28:31], v[164:167], v[188:191], v[28:31]
	v_mfma_f32_16x16x32_bf16 v[24:27], v[172:175], v[188:191], v[24:27]
	v_mfma_f32_16x16x32_bf16 v[12:15], v[164:167], v[196:199], v[12:15]
	v_mfma_f32_16x16x32_bf16 v[8:11], v[172:175], v[196:199], v[8:11]
	v_mfma_f32_16x16x32_bf16 v[4:7], v[164:167], v[226:229], v[4:7]
	v_mfma_f32_16x16x32_bf16 v[0:3], v[172:175], v[226:229], v[0:3]
	v_mfma_f32_16x16x32_bf16 v[44:47], v[168:171], v[184:187], v[44:47]
	v_mfma_f32_16x16x32_bf16 v[40:43], v[176:179], v[184:187], v[40:43]
	v_mfma_f32_16x16x32_bf16 v[28:31], v[168:171], v[192:195], v[28:31]
	v_mfma_f32_16x16x32_bf16 v[24:27], v[176:179], v[192:195], v[24:27]
	v_mfma_f32_16x16x32_bf16 v[12:15], v[168:171], v[222:225], v[12:15]
	v_mfma_f32_16x16x32_bf16 v[8:11], v[176:179], v[222:225], v[8:11]
	v_mfma_f32_16x16x32_bf16 v[4:7], v[168:171], v[230:233], v[4:7]
	v_mfma_f32_16x16x32_bf16 v[0:3], v[176:179], v[230:233], v[0:3]
	s_setprio 0
	s_barrier
; #define PG8_STAGE(bufoff, gbase, voff) do { _Pragma("unroll") for (int _i = 0; _i < 2; ++_i) \
;         __builtin_amdgcn_global_load_lds((const unsigned*)((const char*)(gbase) + (voff)[_i]), (PG8_LAS unsigned*)(lds + (bufoff) + ldsw + _i * 8192), 16, 0, 0); } while (0)
; #define PG8_LDA(dst, b, h) do { _Pragma("unroll") for (int m = 0; m < 4; ++m) _Pragma("unroll") for (int k = 0; k < 2; ++k) dst[m][k] = *(const PG8_LAS bf16x8*)(lds + PG8_SA(b, h) + aoff + m * 2048 + k * 1024); } while (0)
; #define PG8_LDB(dst, b, h) do { _Pragma("unroll") for (int n = 0; n < 2; ++n) _Pragma("unroll") for (int k = 0; k < 2; ++k) dst[n][k] = *(const PG8_LAS bf16x8*)(lds + PG8_SB(b, h) + boff + n * 2048 + k * 1024); } while (0)
; #define PG8_MMA(ai, bj, At, Bt) do { __builtin_amdgcn_s_setprio(1); _Pragma("unroll") for (int m = 0; m < 4; ++m) _Pragma("unroll") for (int n = 0; n < 2; ++n) _Pragma("unroll") for (int k = 0; k < 2; ++k) \
;         acc[ai][bj][m][n] = __builtin_amdgcn_mfma_f32_16x16x32_bf16(Bt[n][k], At[m][k], acc[ai][bj][m][n], 0, 0, 0); __builtin_amdgcn_s_setprio(0); } while (0)
; #define PG8_WAIT_V(n) asm volatile("s_waitcnt vmcnt(" #n ")" ::: "memory")
; #define PG8_WAIT_L(n) asm volatile("s_waitcnt lgkmcnt(" #n ")" ::: "memory")
; #define PG8_BAR __builtin_amdgcn_s_barrier()
; #define PG8_SCHED __builtin_amdgcn_sched_barrier(0)
; template <class Epi, class Sched, bool ALIGN_EPI = false, bool SP2 = false>
; __device__ __forceinline__ void gemm_phase(PG8_LAS unsigned char* lds, const Gemm g, const Sched& S, const Epi& E) {
;     ...
;             PG8_LDB(B0, 1, 0); PG8_LDB(B1, 1, 1); PG8_SCHED; PG8_LDA(At, 1, 0); PG8_STAGE(PG8_SA(0, 1), a2 + hstep, voffA);
;             PG8_WAIT_V(8); PG8_WAIT_L(0); PG8_BAR; PG8_MMA(0, 0, At, B0); PG8_MMA(0, 1, At, B1); PG8_BAR; PG8_SCHED;
;             PG8_LDA(At, 1, 1); PG8_STAGE(PG8_SB(1, 0), b3, voffB); PG8_STAGE(PG8_SB(1, 1), b3 + hstep, voffB); PG8_STAGE(PG8_SA(1, 0), a3, voffA);
;             PG8_WAIT_V(8); PG8_WAIT_L(0); PG8_BAR; PG8_MMA(1, 0, At, B0); PG8_MMA(1, 1, At, B1); PG8_BAR; PG8_SCHED;
;     ...
;         if constexpr (ALIGN_EPI) { if (wr == 0) PG8_BAR; }
	s_add_i32 s88, 0, 0x18000
	s_add_i32 s89, 0, 0x1c000
	ds_read_b128 v[142:145], v200 offset:32768
	ds_read_b128 v[146:149], v200 offset:33792
	ds_read_b128 v[150:153], v200 offset:34816
	ds_read_b128 v[154:157], v200 offset:35840
	ds_read_b128 v[164:167], v200 offset:49152
	ds_read_b128 v[168:171], v200 offset:50176
	ds_read_b128 v[172:175], v200 offset:51200
	ds_read_b128 v[176:179], v200 offset:52224
	s_add_u32 s52, s52, 0x80000
	s_addc_u32 s53, s53, 0
	s_mov_b32 m0, s56
	ds_read_b128 v[180:183], v141 offset:32768
	ds_read_b128 v[184:187], v141 offset:33792
	ds_read_b128 v[188:191], v141 offset:34816
	ds_read_b128 v[192:195], v141 offset:35840
	ds_read_b128 v[196:199], v141 offset:36864
	ds_read_b128 v[222:225], v141 offset:37888
	ds_read_b128 v[226:229], v141 offset:38912
	ds_read_b128 v[230:233], v141 offset:39936
	global_load_lds_dwordx4 v132, s[52:53]
	s_mov_b32 m0, s57
	s_nop 0
	global_load_lds_dwordx4 v130, s[52:53]
	s_waitcnt vmcnt(8)
	s_waitcnt lgkmcnt(0)
	s_barrier
	s_setprio 1
	s_waitcnt lgkmcnt(0)
	v_mfma_f32_16x16x32_bf16 v[124:127], v[142:145], v[180:183], v[124:127]
	v_mfma_f32_16x16x32_bf16 v[120:123], v[150:153], v[180:183], v[120:123]
	v_mfma_f32_16x16x32_bf16 v[116:119], v[142:145], v[188:191], v[116:119]
	v_mfma_f32_16x16x32_bf16 v[112:115], v[150:153], v[188:191], v[112:115]
	v_mfma_f32_16x16x32_bf16 v[100:103], v[142:145], v[196:199], v[100:103]
	v_mfma_f32_16x16x32_bf16 v[96:99], v[150:153], v[196:199], v[96:99]
	v_mfma_f32_16x16x32_bf16 v[84:87], v[142:145], v[226:229], v[84:87]
	v_mfma_f32_16x16x32_bf16 v[80:83], v[150:153], v[226:229], v[80:83]
	v_mfma_f32_16x16x32_bf16 v[124:127], v[146:149], v[184:187], v[124:127]
	v_mfma_f32_16x16x32_bf16 v[120:123], v[154:157], v[184:187], v[120:123]
	v_mfma_f32_16x16x32_bf16 v[116:119], v[146:149], v[192:195], v[116:119]
	v_mfma_f32_16x16x32_bf16 v[112:115], v[154:157], v[192:195], v[112:115]
	v_mfma_f32_16x16x32_bf16 v[100:103], v[146:149], v[222:225], v[100:103]
	v_mfma_f32_16x16x32_bf16 v[96:99], v[154:157], v[222:225], v[96:99]
	v_mfma_f32_16x16x32_bf16 v[84:87], v[146:149], v[230:233], v[84:87]
	v_mfma_f32_16x16x32_bf16 v[80:83], v[154:157], v[230:233], v[80:83]
	v_mfma_f32_16x16x32_bf16 v[108:111], v[164:167], v[180:183], v[108:111]
	v_mfma_f32_16x16x32_bf16 v[104:107], v[172:175], v[180:183], v[104:107]
	v_mfma_f32_16x16x32_bf16 v[92:95], v[164:167], v[188:191], v[92:95]
	v_mfma_f32_16x16x32_bf16 v[88:91], v[172:175], v[188:191], v[88:91]
	v_mfma_f32_16x16x32_bf16 v[76:79], v[164:167], v[196:199], v[76:79]
	v_mfma_f32_16x16x32_bf16 v[72:75], v[172:175], v[196:199], v[72:75]
	v_mfma_f32_16x16x32_bf16 v[68:71], v[164:167], v[226:229], v[68:71]
	v_mfma_f32_16x16x32_bf16 v[64:67], v[172:175], v[226:229], v[64:67]
	v_mfma_f32_16x16x32_bf16 v[108:111], v[168:171], v[184:187], v[108:111]
	v_mfma_f32_16x16x32_bf16 v[104:107], v[176:179], v[184:187], v[104:107]
	v_mfma_f32_16x16x32_bf16 v[92:95], v[168:171], v[192:195], v[92:95]
	v_mfma_f32_16x16x32_bf16 v[88:91], v[176:179], v[192:195], v[88:91]
	v_mfma_f32_16x16x32_bf16 v[76:79], v[168:171], v[222:225], v[76:79]
	v_mfma_f32_16x16x32_bf16 v[72:75], v[176:179], v[222:225], v[72:75]
	v_mfma_f32_16x16x32_bf16 v[68:71], v[168:171], v[230:233], v[68:71]
	v_mfma_f32_16x16x32_bf16 v[64:67], v[176:179], v[230:233], v[64:67]
	s_setprio 0
	s_barrier
	s_add_i32 s52, s88, s28
	s_mov_b32 m0, s52
	ds_read_b128 v[180:183], v141 offset:49152
	ds_read_b128 v[184:187], v141 offset:50176
	ds_read_b128 v[188:191], v141 offset:51200
	ds_read_b128 v[192:195], v141 offset:52224
	ds_read_b128 v[196:199], v141 offset:53248
	ds_read_b128 v[222:225], v141 offset:54272
	ds_read_b128 v[226:229], v141 offset:55296
	ds_read_b128 v[230:233], v141 offset:56320
	s_add_u32 s4, s4, 0x80
	s_addc_u32 s5, s5, 0
	global_load_lds_dwordx4 v160, s[4:5]
	s_add_i32 m0, s52, 0x2000
	s_add_i32 s52, s89, s28
	global_load_lds_dwordx4 v128, s[4:5]
	s_add_u32 s4, s4, 0x80000
	s_addc_u32 s5, s5, 0
	s_mov_b32 m0, s52
	s_nop 0
	global_load_lds_dwordx4 v160, s[4:5]
	s_add_i32 m0, s52, 0x2000
	s_nop 0
	global_load_lds_dwordx4 v128, s[4:5]
	s_mov_b32 m0, s24
	s_nop 0
	global_load_lds_dwordx4 v132, s[98:99]
	s_mov_b32 m0, s59
	s_nop 0
	global_load_lds_dwordx4 v130, s[98:99]
	s_waitcnt vmcnt(8)
	s_waitcnt lgkmcnt(0)
	s_barrier
	s_setprio 1
	s_waitcnt lgkmcnt(0)
	v_mfma_f32_16x16x32_bf16 v[60:63], v[142:145], v[180:183], v[60:63]
	v_mfma_f32_16x16x32_bf16 v[56:59], v[150:153], v[180:183], v[56:59]
	v_mfma_f32_16x16x32_bf16 v[52:55], v[142:145], v[188:191], v[52:55]
	v_mfma_f32_16x16x32_bf16 v[48:51], v[150:153], v[188:191], v[48:51]
	v_mfma_f32_16x16x32_bf16 v[36:39], v[142:145], v[196:199], v[36:39]
	v_mfma_f32_16x16x32_bf16 v[32:35], v[150:153], v[196:199], v[32:35]
	v_mfma_f32_16x16x32_bf16 v[20:23], v[142:145], v[226:229], v[20:23]
	v_mfma_f32_16x16x32_bf16 v[16:19], v[150:153], v[226:229], v[16:19]
	v_mfma_f32_16x16x32_bf16 v[60:63], v[146:149], v[184:187], v[60:63]
	v_mfma_f32_16x16x32_bf16 v[56:59], v[154:157], v[184:187], v[56:59]
	v_mfma_f32_16x16x32_bf16 v[52:55], v[146:149], v[192:195], v[52:55]
	v_mfma_f32_16x16x32_bf16 v[48:51], v[154:157], v[192:195], v[48:51]
	v_mfma_f32_16x16x32_bf16 v[36:39], v[146:149], v[222:225], v[36:39]
	v_mfma_f32_16x16x32_bf16 v[32:35], v[154:157], v[222:225], v[32:35]
	v_mfma_f32_16x16x32_bf16 v[20:23], v[146:149], v[230:233], v[20:23]
	v_mfma_f32_16x16x32_bf16 v[16:19], v[154:157], v[230:233], v[16:19]
	v_mfma_f32_16x16x32_bf16 v[44:47], v[164:167], v[180:183], v[44:47]
	v_mfma_f32_16x16x32_bf16 v[40:43], v[172:175], v[180:183], v[40:43]
	v_mfma_f32_16x16x32_bf16 v[28:31], v[164:167], v[188:191], v[28:31]
	v_mfma_f32_16x16x32_bf16 v[24:27], v[172:175], v[188:191], v[24:27]
	v_mfma_f32_16x16x32_bf16 v[12:15], v[164:167], v[196:199], v[12:15]
	v_mfma_f32_16x16x32_bf16 v[8:11], v[172:175], v[196:199], v[8:11]
	v_mfma_f32_16x16x32_bf16 v[4:7], v[164:167], v[226:229], v[4:7]
	v_mfma_f32_16x16x32_bf16 v[0:3], v[172:175], v[226:229], v[0:3]
	v_mfma_f32_16x16x32_bf16 v[44:47], v[168:171], v[184:187], v[44:47]
	v_mfma_f32_16x16x32_bf16 v[40:43], v[176:179], v[184:187], v[40:43]
	v_mfma_f32_16x16x32_bf16 v[28:31], v[168:171], v[192:195], v[28:31]
	v_mfma_f32_16x16x32_bf16 v[24:27], v[176:179], v[192:195], v[24:27]
	v_mfma_f32_16x16x32_bf16 v[12:15], v[168:171], v[222:225], v[12:15]
	v_mfma_f32_16x16x32_bf16 v[8:11], v[176:179], v[222:225], v[8:11]
	v_mfma_f32_16x16x32_bf16 v[4:7], v[168:171], v[230:233], v[4:7]
	v_mfma_f32_16x16x32_bf16 v[0:3], v[176:179], v[230:233], v[0:3]
	s_setprio 0
	s_barrier
	s_add_i32 s87, s87, 2
	s_add_u32 s80, s80, 0x100
	s_addc_u32 s81, s81, 0
	s_add_u32 s85, s85, 0x100
	s_addc_u32 s86, s86, 0
	s_cmp_gt_u32 s87, 29
	s_cbranch_scc0 .LBB0_25
	s_and_b64 vcc, exec, s[42:43]
	s_cbranch_vccz .LBB0_28
	s_barrier

; #define PG8_STAGE(bufoff, gbase, voff) do { _Pragma("unroll") for (int _i = 0; _i < 2; ++_i) \
;         __builtin_amdgcn_global_load_lds((const unsigned*)((const char*)(gbase) + (voff)[_i]), (PG8_LAS unsigned*)(lds + (bufoff) + ldsw + _i * 8192), 16, 0, 0); } while (0)
; #define PG8_LDA(dst, b, h) do { _Pragma("unroll") for (int m = 0; m < 4; ++m) _Pragma("unroll") for (int k = 0; k < 2; ++k) dst[m][k] = *(const PG8_LAS bf16x8*)(lds + PG8_SA(b, h) + aoff + m * 2048 + k * 1024); } while (0)
; #define PG8_LDB(dst, b, h) do { _Pragma("unroll") for (int n = 0; n < 2; ++n) _Pragma("unroll") for (int k = 0; k < 2; ++k) dst[n][k] = *(const PG8_LAS bf16x8*)(lds + PG8_SB(b, h) + boff + n * 2048 + k * 1024); } while (0)
; #define PG8_MMA(ai, bj, At, Bt) do { __builtin_amdgcn_s_setprio(1); _Pragma("unroll") for (int m = 0; m < 4; ++m) _Pragma("unroll") for (int n = 0; n < 2; ++n) _Pragma("unroll") for (int k = 0; k < 2; ++k) \
;         acc[ai][bj][m][n] = __builtin_amdgcn_mfma_f32_16x16x32_bf16(Bt[n][k], At[m][k], acc[ai][bj][m][n], 0, 0, 0); __builtin_amdgcn_s_setprio(0); } while (0)
; #define PG8_WAIT_V(n) asm volatile("s_waitcnt vmcnt(" #n ")" ::: "memory")
; #define PG8_WAIT_L(n) asm volatile("s_waitcnt lgkmcnt(" #n ")" ::: "memory")
; template <class Epi, class Sched, bool ALIGN_EPI = false, bool SP2 = false>
; __device__ __forceinline__ void gemm_phase(PG8_LAS unsigned char* lds, const Gemm g, const Sched& S, const Epi& E) {
;     ...
;             const bool last = (t == nt - 2);
;             const char* a1 = cA + (size_t)(t + 1) * kstep;
;             const char* a2 = last ? nA : cA + (size_t)(t + 2) * kstep; const char* b2 = last ? nB : cB + (size_t)(t + 2) * kstep;
;             const char* a3 = a2 + kstep; const char* b3 = b2 + kstep;
;             if (last && has_next) S.a_ready(nxt);
;             if constexpr (SP2) {
;             PG8_LDB(B0, 0, 0); PG8_LDB(B1, 0, 1); PG8_SCHED; PG8_LDA(At, 0, 0); PG8_STAGE(PG8_SA(1, 1), a1 + hstep, voffA);
;             PG8_WAIT_V(8); PG8_WAIT_L(0); PG8_BAR; PG8_MMA(0, 0, At, B0); PG8_MMA(0, 1, At, B1); PG8_BAR; PG8_SCHED;
;             PG8_LDA(At, 0, 1); PG8_STAGE(PG8_SB(0, 0), b2, voffB); PG8_STAGE(PG8_SB(0, 1), b2 + hstep, voffB); PG8_STAGE(PG8_SA(0, 0), a2, voffA);
;             PG8_WAIT_V(8); PG8_WAIT_L(0); PG8_BAR; PG8_MMA(1, 0, At, B0); PG8_MMA(1, 1, At, B1); PG8_BAR; PG8_SCHED;
.LBB0_52:
	s_add_i32 s84, 0, 0x10000
	s_add_i32 s85, 0, 0x14000
	ds_read_b128 v[142:145], v200
	ds_read_b128 v[146:149], v200 offset:1024
	ds_read_b128 v[150:153], v200 offset:2048
	ds_read_b128 v[154:157], v200 offset:3072
	ds_read_b128 v[164:167], v200 offset:16384
	ds_read_b128 v[168:171], v200 offset:17408
	ds_read_b128 v[172:175], v200 offset:18432
	ds_read_b128 v[176:179], v200 offset:19456
	s_add_i32 m0, s28, 0xc000
	ds_read_b128 v[180:183], v141
	ds_read_b128 v[184:187], v141 offset:1024
	ds_read_b128 v[188:191], v141 offset:2048
	ds_read_b128 v[192:195], v141 offset:3072
	ds_read_b128 v[196:199], v141 offset:4096
	ds_read_b128 v[222:225], v141 offset:5120
	ds_read_b128 v[226:229], v141 offset:6144
	ds_read_b128 v[230:233], v141 offset:7168
	global_load_lds_dwordx4 v134, s[72:73]
	s_add_i32 m0, s28, 0xe000
	s_nop 0
	global_load_lds_dwordx4 v136, s[72:73]
	s_add_u32 s4, s72, 0x100
	s_addc_u32 s5, s73, 0
	s_cmpk_eq_i32 s83, 0x54
	s_cselect_b32 s57, s45, s5
	s_cselect_b32 s56, s44, s4
	s_cselect_b32 s53, s55, s82
	s_cselect_b32 s52, s54, s81
	s_waitcnt vmcnt(8)
	s_waitcnt lgkmcnt(0)
	s_barrier
	s_setprio 1
	s_waitcnt lgkmcnt(0)
	v_mfma_f32_16x16x32_bf16 v[124:127], v[142:145], v[180:183], v[124:127]
	v_mfma_f32_16x16x32_bf16 v[120:123], v[150:153], v[180:183], v[120:123]
	v_mfma_f32_16x16x32_bf16 v[116:119], v[142:145], v[188:191], v[116:119]
	v_mfma_f32_16x16x32_bf16 v[112:115], v[150:153], v[188:191], v[112:115]
	v_mfma_f32_16x16x32_bf16 v[100:103], v[142:145], v[196:199], v[100:103]
	v_mfma_f32_16x16x32_bf16 v[96:99], v[150:153], v[196:199], v[96:99]
	v_mfma_f32_16x16x32_bf16 v[84:87], v[142:145], v[226:229], v[84:87]
	v_mfma_f32_16x16x32_bf16 v[80:83], v[150:153], v[226:229], v[80:83]
	v_mfma_f32_16x16x32_bf16 v[124:127], v[146:149], v[184:187], v[124:127]
	v_mfma_f32_16x16x32_bf16 v[120:123], v[154:157], v[184:187], v[120:123]
	v_mfma_f32_16x16x32_bf16 v[116:119], v[146:149], v[192:195], v[116:119]
	v_mfma_f32_16x16x32_bf16 v[112:115], v[154:157], v[192:195], v[112:115]
	v_mfma_f32_16x16x32_bf16 v[100:103], v[146:149], v[222:225], v[100:103]
	v_mfma_f32_16x16x32_bf16 v[96:99], v[154:157], v[222:225], v[96:99]
	v_mfma_f32_16x16x32_bf16 v[84:87], v[146:149], v[230:233], v[84:87]
	v_mfma_f32_16x16x32_bf16 v[80:83], v[154:157], v[230:233], v[80:83]
	v_mfma_f32_16x16x32_bf16 v[108:111], v[164:167], v[180:183], v[108:111]
	v_mfma_f32_16x16x32_bf16 v[104:107], v[172:175], v[180:183], v[104:107]
	v_mfma_f32_16x16x32_bf16 v[92:95], v[164:167], v[188:191], v[92:95]
	v_mfma_f32_16x16x32_bf16 v[88:91], v[172:175], v[188:191], v[88:91]
	v_mfma_f32_16x16x32_bf16 v[76:79], v[164:167], v[196:199], v[76:79]
	v_mfma_f32_16x16x32_bf16 v[72:75], v[172:175], v[196:199], v[72:75]
	v_mfma_f32_16x16x32_bf16 v[68:71], v[164:167], v[226:229], v[68:71]
	v_mfma_f32_16x16x32_bf16 v[64:67], v[172:175], v[226:229], v[64:67]
	v_mfma_f32_16x16x32_bf16 v[108:111], v[168:171], v[184:187], v[108:111]
	v_mfma_f32_16x16x32_bf16 v[104:107], v[176:179], v[184:187], v[104:107]
	v_mfma_f32_16x16x32_bf16 v[92:95], v[168:171], v[192:195], v[92:95]
	v_mfma_f32_16x16x32_bf16 v[88:91], v[176:179], v[192:195], v[88:91]
	v_mfma_f32_16x16x32_bf16 v[76:79], v[168:171], v[222:225], v[76:79]
	v_mfma_f32_16x16x32_bf16 v[72:75], v[176:179], v[222:225], v[72:75]
	v_mfma_f32_16x16x32_bf16 v[68:71], v[168:171], v[230:233], v[68:71]
	v_mfma_f32_16x16x32_bf16 v[64:67], v[176:179], v[230:233], v[64:67]
	s_setprio 0
	s_barrier
	s_add_i32 s72, s84, s24
	s_mov_b32 m0, s72
	ds_read_b128 v[180:183], v141 offset:16384
	ds_read_b128 v[184:187], v141 offset:17408
	ds_read_b128 v[188:191], v141 offset:18432
	ds_read_b128 v[192:195], v141 offset:19456
	ds_read_b128 v[196:199], v141 offset:20480
	ds_read_b128 v[222:225], v141 offset:21504
	ds_read_b128 v[226:229], v141 offset:22528
	ds_read_b128 v[230:233], v141 offset:23552
	global_load_lds_dwordx4 v160, s[52:53]
	s_add_i32 m0, s72, 0x2000
	s_add_u32 s72, s52, 0x160000
	s_addc_u32 s73, s53, 0
	s_add_i32 s84, s85, s24
	global_load_lds_dwordx4 v128, s[52:53]
	s_mov_b32 m0, s84
	s_nop 0
	global_load_lds_dwordx4 v160, s[72:73]
	s_add_i32 m0, s84, 0x2000
	s_nop 0
	global_load_lds_dwordx4 v128, s[72:73]
	s_mov_b32 m0, s28
	s_nop 0
	global_load_lds_dwordx4 v132, s[56:57]
	s_mov_b32 m0, s29
	s_nop 0
	global_load_lds_dwordx4 v130, s[56:57]
	s_add_u32 s98, s56, 0x80
	s_addc_u32 s99, s57, 0
	s_waitcnt vmcnt(8)
	s_waitcnt lgkmcnt(0)
	s_barrier
	s_setprio 1
	s_waitcnt lgkmcnt(0)
	v_mfma_f32_16x16x32_bf16 v[60:63], v[142:145], v[180:183], v[60:63]
	v_mfma_f32_16x16x32_bf16 v[56:59], v[150:153], v[180:183], v[56:59]
	v_mfma_f32_16x16x32_bf16 v[52:55], v[142:145], v[188:191], v[52:55]
	v_mfma_f32_16x16x32_bf16 v[48:51], v[150:153], v[188:191], v[48:51]
	v_mfma_f32_16x16x32_bf16 v[36:39], v[142:145], v[196:199], v[36:39]
	v_mfma_f32_16x16x32_bf16 v[32:35], v[150:153], v[196:199], v[32:35]
	v_mfma_f32_16x16x32_bf16 v[20:23], v[142:145], v[226:229], v[20:23]
	v_mfma_f32_16x16x32_bf16 v[16:19], v[150:153], v[226:229], v[16:19]
	v_mfma_f32_16x16x32_bf16 v[60:63], v[146:149], v[184:187], v[60:63]
	v_mfma_f32_16x16x32_bf16 v[56:59], v[154:157], v[184:187], v[56:59]
	v_mfma_f32_16x16x32_bf16 v[52:55], v[146:149], v[192:195], v[52:55]
	v_mfma_f32_16x16x32_bf16 v[48:51], v[154:157], v[192:195], v[48:51]
	v_mfma_f32_16x16x32_bf16 v[36:39], v[146:149], v[222:225], v[36:39]
	v_mfma_f32_16x16x32_bf16 v[32:35], v[154:157], v[222:225], v[32:35]
	v_mfma_f32_16x16x32_bf16 v[20:23], v[146:149], v[230:233], v[20:23]
	v_mfma_f32_16x16x32_bf16 v[16:19], v[154:157], v[230:233], v[16:19]
	v_mfma_f32_16x16x32_bf16 v[44:47], v[164:167], v[180:183], v[44:47]
	v_mfma_f32_16x16x32_bf16 v[40:43], v[172:175], v[180:183], v[40:43]
	v_mfma_f32_16x16x32_bf16 v[28:31], v[164:167], v[188:191], v[28:31]
	v_mfma_f32_16x16x32_bf16 v[24:27], v[172:175], v[188:191], v[24:27]
	v_mfma_f32_16x16x32_bf16 v[12:15], v[164:167], v[196:199], v[12:15]
	v_mfma_f32_16x16x32_bf16 v[8:11], v[172:175], v[196:199], v[8:11]
	v_mfma_f32_16x16x32_bf16 v[4:7], v[164:167], v[226:229], v[4:7]
	v_mfma_f32_16x16x32_bf16 v[0:3], v[172:175], v[226:229], v[0:3]
	v_mfma_f32_16x16x32_bf16 v[44:47], v[168:171], v[184:187], v[44:47]
	v_mfma_f32_16x16x32_bf16 v[40:43], v[176:179], v[184:187], v[40:43]
	v_mfma_f32_16x16x32_bf16 v[28:31], v[168:171], v[192:195], v[28:31]
	v_mfma_f32_16x16x32_bf16 v[24:27], v[176:179], v[192:195], v[24:27]
	v_mfma_f32_16x16x32_bf16 v[12:15], v[168:171], v[222:225], v[12:15]
	v_mfma_f32_16x16x32_bf16 v[8:11], v[176:179], v[222:225], v[8:11]
	v_mfma_f32_16x16x32_bf16 v[4:7], v[168:171], v[230:233], v[4:7]
	v_mfma_f32_16x16x32_bf16 v[0:3], v[176:179], v[230:233], v[0:3]
	s_setprio 0
	s_barrier
; #define PG8_STAGE(bufoff, gbase, voff) do { _Pragma("unroll") for (int _i = 0; _i < 2; ++_i) \
;         __builtin_amdgcn_global_load_lds((const unsigned*)((const char*)(gbase) + (voff)[_i]), (PG8_LAS unsigned*)(lds + (bufoff) + ldsw + _i * 8192), 16, 0, 0); } while (0)
; #define PG8_LDA(dst, b, h) do { _Pragma("unroll") for (int m = 0; m < 4; ++m) _Pragma("unroll") for (int k = 0; k < 2; ++k) dst[m][k] = *(const PG8_LAS bf16x8*)(lds + PG8_SA(b, h) + aoff + m * 2048 + k * 1024); } while (0)
; #define PG8_LDB(dst, b, h) do { _Pragma("unroll") for (int n = 0; n < 2; ++n) _Pragma("unroll") for (int k = 0; k < 2; ++k) dst[n][k] = *(const PG8_LAS bf16x8*)(lds + PG8_SB(b, h) + boff + n * 2048 + k * 1024); } while (0)
; #define PG8_MMA(ai, bj, At, Bt) do { __builtin_amdgcn_s_setprio(1); _Pragma("unroll") for (int m = 0; m < 4; ++m) _Pragma("unroll") for (int n = 0; n < 2; ++n) _Pragma("unroll") for (int k = 0; k < 2; ++k) \
;         acc[ai][bj][m][n] = __builtin_amdgcn_mfma_f32_16x16x32_bf16(Bt[n][k], At[m][k], acc[ai][bj][m][n], 0, 0, 0); __builtin_amdgcn_s_setprio(0); } while (0)
; #define PG8_WAIT_V(n) asm volatile("s_waitcnt vmcnt(" #n ")" ::: "memory")
; #define PG8_WAIT_L(n) asm volatile("s_waitcnt lgkmcnt(" #n ")" ::: "memory")
; #define PG8_BAR __builtin_amdgcn_s_barrier()
; #define PG8_SCHED __builtin_amdgcn_sched_barrier(0)
; template <class Epi, class Sched, bool ALIGN_EPI = false, bool SP2 = false>
; __device__ __forceinline__ void gemm_phase(PG8_LAS unsigned char* lds, const Gemm g, const Sched& S, const Epi& E) {
;     ...
;             PG8_LDB(B0, 1, 0); PG8_LDB(B1, 1, 1); PG8_SCHED; PG8_LDA(At, 1, 0); PG8_STAGE(PG8_SA(0, 1), a2 + hstep, voffA);
;             PG8_WAIT_V(8); PG8_WAIT_L(0); PG8_BAR; PG8_MMA(0, 0, At, B0); PG8_MMA(0, 1, At, B1); PG8_BAR; PG8_SCHED;
;             PG8_LDA(At, 1, 1); PG8_STAGE(PG8_SB(1, 0), b3, voffB); PG8_STAGE(PG8_SB(1, 1), b3 + hstep, voffB); PG8_STAGE(PG8_SA(1, 0), a3, voffA);
;             PG8_WAIT_V(8); PG8_WAIT_L(0); PG8_BAR; PG8_MMA(1, 0, At, B0); PG8_MMA(1, 1, At, B1); PG8_BAR; PG8_SCHED;
;     ...
;         if constexpr (ALIGN_EPI) { if (wr == 0) PG8_BAR; }
	s_add_i32 s72, 0, 0x18000
	s_add_i32 s73, 0, 0x1c000
	ds_read_b128 v[142:145], v200 offset:32768
	ds_read_b128 v[146:149], v200 offset:33792
	ds_read_b128 v[150:153], v200 offset:34816
	ds_read_b128 v[154:157], v200 offset:35840
	ds_read_b128 v[164:167], v200 offset:49152
	ds_read_b128 v[168:171], v200 offset:50176
	ds_read_b128 v[172:175], v200 offset:51200
	ds_read_b128 v[176:179], v200 offset:52224
	s_add_u32 s56, s56, 0x160000
	s_addc_u32 s57, s57, 0
	s_mov_b32 m0, s59
	ds_read_b128 v[180:183], v141 offset:32768
	ds_read_b128 v[184:187], v141 offset:33792
	ds_read_b128 v[188:191], v141 offset:34816
	ds_read_b128 v[192:195], v141 offset:35840
	ds_read_b128 v[196:199], v141 offset:36864
	ds_read_b128 v[222:225], v141 offset:37888
	ds_read_b128 v[226:229], v141 offset:38912
	ds_read_b128 v[230:233], v141 offset:39936
	global_load_lds_dwordx4 v132, s[56:57]
	s_mov_b32 m0, s63
	s_nop 0
	global_load_lds_dwordx4 v130, s[56:57]
	s_waitcnt vmcnt(8)
	s_waitcnt lgkmcnt(0)
	s_barrier
	s_setprio 1
	s_waitcnt lgkmcnt(0)
	v_mfma_f32_16x16x32_bf16 v[124:127], v[142:145], v[180:183], v[124:127]
	v_mfma_f32_16x16x32_bf16 v[120:123], v[150:153], v[180:183], v[120:123]
	v_mfma_f32_16x16x32_bf16 v[116:119], v[142:145], v[188:191], v[116:119]
	v_mfma_f32_16x16x32_bf16 v[112:115], v[150:153], v[188:191], v[112:115]
	v_mfma_f32_16x16x32_bf16 v[100:103], v[142:145], v[196:199], v[100:103]
	v_mfma_f32_16x16x32_bf16 v[96:99], v[150:153], v[196:199], v[96:99]
	v_mfma_f32_16x16x32_bf16 v[84:87], v[142:145], v[226:229], v[84:87]
	v_mfma_f32_16x16x32_bf16 v[80:83], v[150:153], v[226:229], v[80:83]
	v_mfma_f32_16x16x32_bf16 v[124:127], v[146:149], v[184:187], v[124:127]
	v_mfma_f32_16x16x32_bf16 v[120:123], v[154:157], v[184:187], v[120:123]
	v_mfma_f32_16x16x32_bf16 v[116:119], v[146:149], v[192:195], v[116:119]
	v_mfma_f32_16x16x32_bf16 v[112:115], v[154:157], v[192:195], v[112:115]
	v_mfma_f32_16x16x32_bf16 v[100:103], v[146:149], v[222:225], v[100:103]
	v_mfma_f32_16x16x32_bf16 v[96:99], v[154:157], v[222:225], v[96:99]
	v_mfma_f32_16x16x32_bf16 v[84:87], v[146:149], v[230:233], v[84:87]
	v_mfma_f32_16x16x32_bf16 v[80:83], v[154:157], v[230:233], v[80:83]
	v_mfma_f32_16x16x32_bf16 v[108:111], v[164:167], v[180:183], v[108:111]
	v_mfma_f32_16x16x32_bf16 v[104:107], v[172:175], v[180:183], v[104:107]
	v_mfma_f32_16x16x32_bf16 v[92:95], v[164:167], v[188:191], v[92:95]
	v_mfma_f32_16x16x32_bf16 v[88:91], v[172:175], v[188:191], v[88:91]
	v_mfma_f32_16x16x32_bf16 v[76:79], v[164:167], v[196:199], v[76:79]
	v_mfma_f32_16x16x32_bf16 v[72:75], v[172:175], v[196:199], v[72:75]
	v_mfma_f32_16x16x32_bf16 v[68:71], v[164:167], v[226:229], v[68:71]
	v_mfma_f32_16x16x32_bf16 v[64:67], v[172:175], v[226:229], v[64:67]
	v_mfma_f32_16x16x32_bf16 v[108:111], v[168:171], v[184:187], v[108:111]
	v_mfma_f32_16x16x32_bf16 v[104:107], v[176:179], v[184:187], v[104:107]
	v_mfma_f32_16x16x32_bf16 v[92:95], v[168:171], v[192:195], v[92:95]
	v_mfma_f32_16x16x32_bf16 v[88:91], v[176:179], v[192:195], v[88:91]
	v_mfma_f32_16x16x32_bf16 v[76:79], v[168:171], v[222:225], v[76:79]
	v_mfma_f32_16x16x32_bf16 v[72:75], v[176:179], v[222:225], v[72:75]
	v_mfma_f32_16x16x32_bf16 v[68:71], v[168:171], v[230:233], v[68:71]
	v_mfma_f32_16x16x32_bf16 v[64:67], v[176:179], v[230:233], v[64:67]
	s_setprio 0
	s_barrier
	s_add_i32 s56, s72, s24
	s_mov_b32 m0, s56
	ds_read_b128 v[180:183], v141 offset:49152
	ds_read_b128 v[184:187], v141 offset:50176
	ds_read_b128 v[188:191], v141 offset:51200
	ds_read_b128 v[192:195], v141 offset:52224
	ds_read_b128 v[196:199], v141 offset:53248
	ds_read_b128 v[222:225], v141 offset:54272
	ds_read_b128 v[226:229], v141 offset:55296
	ds_read_b128 v[230:233], v141 offset:56320
	s_add_u32 s52, s52, 0x80
	s_addc_u32 s53, s53, 0
	global_load_lds_dwordx4 v160, s[52:53]
	s_add_i32 m0, s56, 0x2000
	s_add_i32 s56, s73, s24
	global_load_lds_dwordx4 v128, s[52:53]
	s_add_u32 s52, s52, 0x160000
	s_addc_u32 s53, s53, 0
	s_mov_b32 m0, s56
	s_nop 0
	global_load_lds_dwordx4 v160, s[52:53]
	s_add_i32 m0, s56, 0x2000
	s_nop 0
	global_load_lds_dwordx4 v128, s[52:53]
	s_mov_b32 m0, s74
	s_nop 0
	global_load_lds_dwordx4 v132, s[98:99]
	s_mov_b32 m0, s75
	s_nop 0
	global_load_lds_dwordx4 v130, s[98:99]
	s_waitcnt vmcnt(8)
	s_waitcnt lgkmcnt(0)
	s_barrier
	s_setprio 1
	s_waitcnt lgkmcnt(0)
	v_mfma_f32_16x16x32_bf16 v[60:63], v[142:145], v[180:183], v[60:63]
	v_mfma_f32_16x16x32_bf16 v[56:59], v[150:153], v[180:183], v[56:59]
	v_mfma_f32_16x16x32_bf16 v[52:55], v[142:145], v[188:191], v[52:55]
	v_mfma_f32_16x16x32_bf16 v[48:51], v[150:153], v[188:191], v[48:51]
	v_mfma_f32_16x16x32_bf16 v[36:39], v[142:145], v[196:199], v[36:39]
	v_mfma_f32_16x16x32_bf16 v[32:35], v[150:153], v[196:199], v[32:35]
	v_mfma_f32_16x16x32_bf16 v[20:23], v[142:145], v[226:229], v[20:23]
	v_mfma_f32_16x16x32_bf16 v[16:19], v[150:153], v[226:229], v[16:19]
	v_mfma_f32_16x16x32_bf16 v[60:63], v[146:149], v[184:187], v[60:63]
	v_mfma_f32_16x16x32_bf16 v[56:59], v[154:157], v[184:187], v[56:59]
	v_mfma_f32_16x16x32_bf16 v[52:55], v[146:149], v[192:195], v[52:55]
	v_mfma_f32_16x16x32_bf16 v[48:51], v[154:157], v[192:195], v[48:51]
	v_mfma_f32_16x16x32_bf16 v[36:39], v[146:149], v[222:225], v[36:39]
	v_mfma_f32_16x16x32_bf16 v[32:35], v[154:157], v[222:225], v[32:35]
	v_mfma_f32_16x16x32_bf16 v[20:23], v[146:149], v[230:233], v[20:23]
	v_mfma_f32_16x16x32_bf16 v[16:19], v[154:157], v[230:233], v[16:19]
	v_mfma_f32_16x16x32_bf16 v[44:47], v[164:167], v[180:183], v[44:47]
	v_mfma_f32_16x16x32_bf16 v[40:43], v[172:175], v[180:183], v[40:43]
	v_mfma_f32_16x16x32_bf16 v[28:31], v[164:167], v[188:191], v[28:31]
	v_mfma_f32_16x16x32_bf16 v[24:27], v[172:175], v[188:191], v[24:27]
	v_mfma_f32_16x16x32_bf16 v[12:15], v[164:167], v[196:199], v[12:15]
	v_mfma_f32_16x16x32_bf16 v[8:11], v[172:175], v[196:199], v[8:11]
	v_mfma_f32_16x16x32_bf16 v[4:7], v[164:167], v[226:229], v[4:7]
	v_mfma_f32_16x16x32_bf16 v[0:3], v[172:175], v[226:229], v[0:3]
	v_mfma_f32_16x16x32_bf16 v[44:47], v[168:171], v[184:187], v[44:47]
	v_mfma_f32_16x16x32_bf16 v[40:43], v[176:179], v[184:187], v[40:43]
	v_mfma_f32_16x16x32_bf16 v[28:31], v[168:171], v[192:195], v[28:31]
	v_mfma_f32_16x16x32_bf16 v[24:27], v[176:179], v[192:195], v[24:27]
	v_mfma_f32_16x16x32_bf16 v[12:15], v[168:171], v[222:225], v[12:15]
	v_mfma_f32_16x16x32_bf16 v[8:11], v[176:179], v[222:225], v[8:11]
	v_mfma_f32_16x16x32_bf16 v[4:7], v[168:171], v[230:233], v[4:7]
	v_mfma_f32_16x16x32_bf16 v[0:3], v[176:179], v[230:233], v[0:3]
	s_setprio 0
	s_barrier
	s_add_i32 s83, s83, 2
	s_add_u32 s81, s81, 0x100
	s_addc_u32 s82, s82, 0
	s_cmpk_gt_u32 s83, 0x55
	s_mov_b64 s[72:73], s[4:5]
	s_cbranch_scc0 .LBB0_52
	s_and_b64 vcc, exec, s[42:43]
	s_cbranch_vccz .LBB0_55
	s_barrier

; #define PG8_STAGE(bufoff, gbase, voff) do { _Pragma("unroll") for (int _i = 0; _i < 2; ++_i) \
;         __builtin_amdgcn_global_load_lds((const unsigned*)((const char*)(gbase) + (voff)[_i]), (PG8_LAS unsigned*)(lds + (bufoff) + ldsw + _i * 8192), 16, 0, 0); } while (0)
; #define PG8_LDA(dst, b, h) do { _Pragma("unroll") for (int m = 0; m < 4; ++m) _Pragma("unroll") for (int k = 0; k < 2; ++k) dst[m][k] = *(const PG8_LAS bf16x8*)(lds + PG8_SA(b, h) + aoff + m * 2048 + k * 1024); } while (0)
; #define PG8_LDB(dst, b, h) do { _Pragma("unroll") for (int n = 0; n < 2; ++n) _Pragma("unroll") for (int k = 0; k < 2; ++k) dst[n][k] = *(const PG8_LAS bf16x8*)(lds + PG8_SB(b, h) + boff + n * 2048 + k * 1024); } while (0)
; #define PG8_MMA(ai, bj, At, Bt) do { __builtin_amdgcn_s_setprio(1); _Pragma("unroll") for (int m = 0; m < 4; ++m) _Pragma("unroll") for (int n = 0; n < 2; ++n) _Pragma("unroll") for (int k = 0; k < 2; ++k) \
;         acc[ai][bj][m][n] = __builtin_amdgcn_mfma_f32_16x16x32_bf16(Bt[n][k], At[m][k], acc[ai][bj][m][n], 0, 0, 0); __builtin_amdgcn_s_setprio(0); } while (0)
; #define PG8_WAIT_V(n) asm volatile("s_waitcnt vmcnt(" #n ")" ::: "memory")
; #define PG8_WAIT_L(n) asm volatile("s_waitcnt lgkmcnt(" #n ")" ::: "memory")
; template <class Epi, class Sched, bool ALIGN_EPI = false, bool SP2 = false>
; __device__ __forceinline__ void gemm_phase(PG8_LAS unsigned char* lds, const Gemm g, const Sched& S, const Epi& E) {
;     ...
;             const bool last = (t == nt - 2);
;             const char* a1 = cA + (size_t)(t + 1) * kstep;
;             const char* a2 = last ? nA : cA + (size_t)(t + 2) * kstep; const char* b2 = last ? nB : cB + (size_t)(t + 2) * kstep;
;             const char* a3 = a2 + kstep; const char* b3 = b2 + kstep;
;             if (last && has_next) S.a_ready(nxt);
;             if constexpr (SP2) {
;             PG8_LDB(B0, 0, 0); PG8_LDB(B1, 0, 1); PG8_SCHED; PG8_LDA(At, 0, 0); PG8_STAGE(PG8_SA(1, 1), a1 + hstep, voffA);
;             PG8_WAIT_V(8); PG8_WAIT_L(0); PG8_BAR; PG8_MMA(0, 0, At, B0); PG8_MMA(0, 1, At, B1); PG8_BAR; PG8_SCHED;
;             PG8_LDA(At, 0, 1); PG8_STAGE(PG8_SB(0, 0), b2, voffB); PG8_STAGE(PG8_SB(0, 1), b2 + hstep, voffB); PG8_STAGE(PG8_SA(0, 0), a2, voffA);
;             PG8_WAIT_V(8); PG8_WAIT_L(0); PG8_BAR; PG8_MMA(1, 0, At, B0); PG8_MMA(1, 1, At, B1); PG8_BAR; PG8_SCHED;
.LBB0_86:
	s_add_i32 s88, 0, 0x10000
	s_add_i32 s90, 0, 0x14000
	ds_read_b128 v[140:143], v200
	ds_read_b128 v[150:153], v200 offset:1024
	ds_read_b128 v[154:157], v200 offset:2048
	ds_read_b128 v[164:167], v200 offset:3072
	ds_read_b128 v[168:171], v200 offset:16384
	ds_read_b128 v[172:175], v200 offset:17408
	ds_read_b128 v[176:179], v200 offset:18432
	ds_read_b128 v[180:183], v200 offset:19456
	s_add_i32 m0, s63, 0xc000
	ds_read_b128 v[184:187], v149
	ds_read_b128 v[188:191], v149 offset:1024
	ds_read_b128 v[192:195], v149 offset:2048
	ds_read_b128 v[196:199], v149 offset:3072
	ds_read_b128 v[222:225], v149 offset:4096
	ds_read_b128 v[226:229], v149 offset:5120
	ds_read_b128 v[230:233], v149 offset:6144
	ds_read_b128 v[234:237], v149 offset:7168
	global_load_lds_dwordx4 v136, s[82:83]
	s_add_i32 m0, s63, 0xe000
	s_nop 0
	global_load_lds_dwordx4 v138, s[82:83]
	s_add_u32 s4, s82, 0xfffc0080
	s_addc_u32 s5, s83, -1
	s_cmp_eq_u32 s87, 12
	s_cselect_b32 s53, s7, s5
	s_cselect_b32 s52, s15, s4
	s_cselect_b32 s5, s24, s43
	s_cselect_b32 s4, s28, s29
	s_waitcnt vmcnt(8)
	s_waitcnt lgkmcnt(0)
	s_barrier
	s_setprio 1
	s_waitcnt lgkmcnt(0)
	v_mfma_f32_16x16x32_bf16 v[124:127], v[140:143], v[184:187], v[124:127]
	v_mfma_f32_16x16x32_bf16 v[120:123], v[154:157], v[184:187], v[120:123]
	v_mfma_f32_16x16x32_bf16 v[108:111], v[140:143], v[192:195], v[108:111]
	v_mfma_f32_16x16x32_bf16 v[104:107], v[154:157], v[192:195], v[104:107]
	v_mfma_f32_16x16x32_bf16 v[92:95], v[140:143], v[222:225], v[92:95]
	v_mfma_f32_16x16x32_bf16 v[88:91], v[154:157], v[222:225], v[88:91]
	v_mfma_f32_16x16x32_bf16 v[76:79], v[140:143], v[230:233], v[76:79]
	v_mfma_f32_16x16x32_bf16 v[72:75], v[154:157], v[230:233], v[72:75]
	v_mfma_f32_16x16x32_bf16 v[124:127], v[150:153], v[188:191], v[124:127]
	v_mfma_f32_16x16x32_bf16 v[120:123], v[164:167], v[188:191], v[120:123]
	v_mfma_f32_16x16x32_bf16 v[108:111], v[150:153], v[196:199], v[108:111]
	v_mfma_f32_16x16x32_bf16 v[104:107], v[164:167], v[196:199], v[104:107]
	v_mfma_f32_16x16x32_bf16 v[92:95], v[150:153], v[226:229], v[92:95]
	v_mfma_f32_16x16x32_bf16 v[88:91], v[164:167], v[226:229], v[88:91]
	v_mfma_f32_16x16x32_bf16 v[76:79], v[150:153], v[234:237], v[76:79]
	v_mfma_f32_16x16x32_bf16 v[72:75], v[164:167], v[234:237], v[72:75]
	v_mfma_f32_16x16x32_bf16 v[116:119], v[168:171], v[184:187], v[116:119]
	v_mfma_f32_16x16x32_bf16 v[112:115], v[176:179], v[184:187], v[112:115]
	v_mfma_f32_16x16x32_bf16 v[100:103], v[168:171], v[192:195], v[100:103]
	v_mfma_f32_16x16x32_bf16 v[96:99], v[176:179], v[192:195], v[96:99]
	v_mfma_f32_16x16x32_bf16 v[84:87], v[168:171], v[222:225], v[84:87]
	v_mfma_f32_16x16x32_bf16 v[80:83], v[176:179], v[222:225], v[80:83]
	v_mfma_f32_16x16x32_bf16 v[68:71], v[168:171], v[230:233], v[68:71]
	v_mfma_f32_16x16x32_bf16 v[64:67], v[176:179], v[230:233], v[64:67]
	v_mfma_f32_16x16x32_bf16 v[116:119], v[172:175], v[188:191], v[116:119]
	v_mfma_f32_16x16x32_bf16 v[112:115], v[180:183], v[188:191], v[112:115]
	v_mfma_f32_16x16x32_bf16 v[100:103], v[172:175], v[196:199], v[100:103]
	v_mfma_f32_16x16x32_bf16 v[96:99], v[180:183], v[196:199], v[96:99]
	v_mfma_f32_16x16x32_bf16 v[84:87], v[172:175], v[226:229], v[84:87]
	v_mfma_f32_16x16x32_bf16 v[80:83], v[180:183], v[226:229], v[80:83]
	v_mfma_f32_16x16x32_bf16 v[68:71], v[172:175], v[234:237], v[68:71]
	v_mfma_f32_16x16x32_bf16 v[64:67], v[180:183], v[234:237], v[64:67]
	s_setprio 0
	s_barrier
	s_add_i32 s88, s88, s59
	s_mov_b32 m0, s88
	ds_read_b128 v[184:187], v149 offset:16384
	ds_read_b128 v[188:191], v149 offset:17408
	ds_read_b128 v[192:195], v149 offset:18432
	ds_read_b128 v[196:199], v149 offset:19456
	ds_read_b128 v[222:225], v149 offset:20480
	ds_read_b128 v[226:229], v149 offset:21504
	ds_read_b128 v[230:233], v149 offset:22528
	ds_read_b128 v[234:237], v149 offset:23552
	global_load_lds_dwordx4 v130, s[4:5]
	s_add_i32 m0, s88, 0x2000
	s_add_u32 s88, s4, 0x40000
	s_addc_u32 s89, s5, 0
	s_add_i32 s90, s90, s59
	global_load_lds_dwordx4 v134, s[4:5]
	s_mov_b32 m0, s90
	s_nop 0
	global_load_lds_dwordx4 v130, s[88:89]
	s_add_i32 m0, s90, 0x2000
	s_nop 0
	global_load_lds_dwordx4 v134, s[88:89]
	s_mov_b32 m0, s63
	s_nop 0
	global_load_lds_dwordx4 v128, s[52:53]
	s_mov_b32 m0, s74
	s_nop 0
	global_load_lds_dwordx4 v132, s[52:53]
	s_add_u32 s98, s52, 0x80
	s_addc_u32 s99, s53, 0
	s_waitcnt vmcnt(8)
	s_waitcnt lgkmcnt(0)
	s_barrier
	s_setprio 1
	s_waitcnt lgkmcnt(0)
	v_mfma_f32_16x16x32_bf16 v[60:63], v[140:143], v[184:187], v[60:63]
	v_mfma_f32_16x16x32_bf16 v[56:59], v[154:157], v[184:187], v[56:59]
	v_mfma_f32_16x16x32_bf16 v[44:47], v[140:143], v[192:195], v[44:47]
	v_mfma_f32_16x16x32_bf16 v[40:43], v[154:157], v[192:195], v[40:43]
	v_mfma_f32_16x16x32_bf16 v[28:31], v[140:143], v[222:225], v[28:31]
	v_mfma_f32_16x16x32_bf16 v[24:27], v[154:157], v[222:225], v[24:27]
	v_mfma_f32_16x16x32_bf16 v[12:15], v[140:143], v[230:233], v[12:15]
	v_mfma_f32_16x16x32_bf16 v[8:11], v[154:157], v[230:233], v[8:11]
	v_mfma_f32_16x16x32_bf16 v[60:63], v[150:153], v[188:191], v[60:63]
	v_mfma_f32_16x16x32_bf16 v[56:59], v[164:167], v[188:191], v[56:59]
	v_mfma_f32_16x16x32_bf16 v[44:47], v[150:153], v[196:199], v[44:47]
	v_mfma_f32_16x16x32_bf16 v[40:43], v[164:167], v[196:199], v[40:43]
	v_mfma_f32_16x16x32_bf16 v[28:31], v[150:153], v[226:229], v[28:31]
	v_mfma_f32_16x16x32_bf16 v[24:27], v[164:167], v[226:229], v[24:27]
	v_mfma_f32_16x16x32_bf16 v[12:15], v[150:153], v[234:237], v[12:15]
	v_mfma_f32_16x16x32_bf16 v[8:11], v[164:167], v[234:237], v[8:11]
	v_mfma_f32_16x16x32_bf16 v[52:55], v[168:171], v[184:187], v[52:55]
	v_mfma_f32_16x16x32_bf16 v[48:51], v[176:179], v[184:187], v[48:51]
	v_mfma_f32_16x16x32_bf16 v[36:39], v[168:171], v[192:195], v[36:39]
	v_mfma_f32_16x16x32_bf16 v[32:35], v[176:179], v[192:195], v[32:35]
	v_mfma_f32_16x16x32_bf16 v[20:23], v[168:171], v[222:225], v[20:23]
	v_mfma_f32_16x16x32_bf16 v[16:19], v[176:179], v[222:225], v[16:19]
	v_mfma_f32_16x16x32_bf16 v[4:7], v[168:171], v[230:233], v[4:7]
	v_mfma_f32_16x16x32_bf16 v[0:3], v[176:179], v[230:233], v[0:3]
	v_mfma_f32_16x16x32_bf16 v[52:55], v[172:175], v[188:191], v[52:55]
	v_mfma_f32_16x16x32_bf16 v[48:51], v[180:183], v[188:191], v[48:51]
	v_mfma_f32_16x16x32_bf16 v[36:39], v[172:175], v[196:199], v[36:39]
	v_mfma_f32_16x16x32_bf16 v[32:35], v[180:183], v[196:199], v[32:35]
	v_mfma_f32_16x16x32_bf16 v[20:23], v[172:175], v[226:229], v[20:23]
	v_mfma_f32_16x16x32_bf16 v[16:19], v[180:183], v[226:229], v[16:19]
	v_mfma_f32_16x16x32_bf16 v[4:7], v[172:175], v[234:237], v[4:7]
	v_mfma_f32_16x16x32_bf16 v[0:3], v[180:183], v[234:237], v[0:3]
	s_setprio 0
	s_barrier
; #define PG8_STAGE(bufoff, gbase, voff) do { _Pragma("unroll") for (int _i = 0; _i < 2; ++_i) \
;         __builtin_amdgcn_global_load_lds((const unsigned*)((const char*)(gbase) + (voff)[_i]), (PG8_LAS unsigned*)(lds + (bufoff) + ldsw + _i * 8192), 16, 0, 0); } while (0)
; #define PG8_LDA(dst, b, h) do { _Pragma("unroll") for (int m = 0; m < 4; ++m) _Pragma("unroll") for (int k = 0; k < 2; ++k) dst[m][k] = *(const PG8_LAS bf16x8*)(lds + PG8_SA(b, h) + aoff + m * 2048 + k * 1024); } while (0)
; #define PG8_LDB(dst, b, h) do { _Pragma("unroll") for (int n = 0; n < 2; ++n) _Pragma("unroll") for (int k = 0; k < 2; ++k) dst[n][k] = *(const PG8_LAS bf16x8*)(lds + PG8_SB(b, h) + boff + n * 2048 + k * 1024); } while (0)
; #define PG8_MMA(ai, bj, At, Bt) do { __builtin_amdgcn_s_setprio(1); _Pragma("unroll") for (int m = 0; m < 4; ++m) _Pragma("unroll") for (int n = 0; n < 2; ++n) _Pragma("unroll") for (int k = 0; k < 2; ++k) \
;         acc[ai][bj][m][n] = __builtin_amdgcn_mfma_f32_16x16x32_bf16(Bt[n][k], At[m][k], acc[ai][bj][m][n], 0, 0, 0); __builtin_amdgcn_s_setprio(0); } while (0)
; #define PG8_WAIT_V(n) asm volatile("s_waitcnt vmcnt(" #n ")" ::: "memory")
; #define PG8_WAIT_L(n) asm volatile("s_waitcnt lgkmcnt(" #n ")" ::: "memory")
; #define PG8_BAR __builtin_amdgcn_s_barrier()
; #define PG8_SCHED __builtin_amdgcn_sched_barrier(0)
; template <class Epi, class Sched, bool ALIGN_EPI = false, bool SP2 = false>
; __device__ __forceinline__ void gemm_phase(PG8_LAS unsigned char* lds, const Gemm g, const Sched& S, const Epi& E) {
;     ...
;             PG8_LDB(B0, 1, 0); PG8_LDB(B1, 1, 1); PG8_SCHED; PG8_LDA(At, 1, 0); PG8_STAGE(PG8_SA(0, 1), a2 + hstep, voffA);
;             PG8_WAIT_V(8); PG8_WAIT_L(0); PG8_BAR; PG8_MMA(0, 0, At, B0); PG8_MMA(0, 1, At, B1); PG8_BAR; PG8_SCHED;
;             PG8_LDA(At, 1, 1); PG8_STAGE(PG8_SB(1, 0), b3, voffB); PG8_STAGE(PG8_SB(1, 1), b3 + hstep, voffB); PG8_STAGE(PG8_SA(1, 0), a3, voffA);
;             PG8_WAIT_V(8); PG8_WAIT_L(0); PG8_BAR; PG8_MMA(1, 0, At, B0); PG8_MMA(1, 1, At, B1); PG8_BAR; PG8_SCHED;
;     ...
;         if constexpr (ALIGN_EPI) { if (wr == 0) PG8_BAR; }
	s_add_i32 s88, 0, 0x18000
	s_add_i32 s89, 0, 0x1c000
	ds_read_b128 v[140:143], v200 offset:32768
	ds_read_b128 v[150:153], v200 offset:33792
	ds_read_b128 v[154:157], v200 offset:34816
	ds_read_b128 v[164:167], v200 offset:35840
	ds_read_b128 v[168:171], v200 offset:49152
	ds_read_b128 v[172:175], v200 offset:50176
	ds_read_b128 v[176:179], v200 offset:51200
	ds_read_b128 v[180:183], v200 offset:52224
	s_add_u32 s52, s52, 0x40000
	s_addc_u32 s53, s53, 0
	s_mov_b32 m0, s75
	ds_read_b128 v[184:187], v149 offset:32768
	ds_read_b128 v[188:191], v149 offset:33792
	ds_read_b128 v[192:195], v149 offset:34816
	ds_read_b128 v[196:199], v149 offset:35840
	ds_read_b128 v[222:225], v149 offset:36864
	ds_read_b128 v[226:229], v149 offset:37888
	ds_read_b128 v[230:233], v149 offset:38912
	ds_read_b128 v[234:237], v149 offset:39936
	global_load_lds_dwordx4 v128, s[52:53]
	s_mov_b32 m0, s81
	s_nop 0
	global_load_lds_dwordx4 v132, s[52:53]
	s_waitcnt vmcnt(8)
	s_waitcnt lgkmcnt(0)
	s_barrier
	s_setprio 1
	s_waitcnt lgkmcnt(0)
	v_mfma_f32_16x16x32_bf16 v[124:127], v[140:143], v[184:187], v[124:127]
	v_mfma_f32_16x16x32_bf16 v[120:123], v[154:157], v[184:187], v[120:123]
	v_mfma_f32_16x16x32_bf16 v[108:111], v[140:143], v[192:195], v[108:111]
	v_mfma_f32_16x16x32_bf16 v[104:107], v[154:157], v[192:195], v[104:107]
	v_mfma_f32_16x16x32_bf16 v[92:95], v[140:143], v[222:225], v[92:95]
	v_mfma_f32_16x16x32_bf16 v[88:91], v[154:157], v[222:225], v[88:91]
	v_mfma_f32_16x16x32_bf16 v[76:79], v[140:143], v[230:233], v[76:79]
	v_mfma_f32_16x16x32_bf16 v[72:75], v[154:157], v[230:233], v[72:75]
	v_mfma_f32_16x16x32_bf16 v[124:127], v[150:153], v[188:191], v[124:127]
	v_mfma_f32_16x16x32_bf16 v[120:123], v[164:167], v[188:191], v[120:123]
	v_mfma_f32_16x16x32_bf16 v[108:111], v[150:153], v[196:199], v[108:111]
	v_mfma_f32_16x16x32_bf16 v[104:107], v[164:167], v[196:199], v[104:107]
	v_mfma_f32_16x16x32_bf16 v[92:95], v[150:153], v[226:229], v[92:95]
	v_mfma_f32_16x16x32_bf16 v[88:91], v[164:167], v[226:229], v[88:91]
	v_mfma_f32_16x16x32_bf16 v[76:79], v[150:153], v[234:237], v[76:79]
	v_mfma_f32_16x16x32_bf16 v[72:75], v[164:167], v[234:237], v[72:75]
	v_mfma_f32_16x16x32_bf16 v[116:119], v[168:171], v[184:187], v[116:119]
	v_mfma_f32_16x16x32_bf16 v[112:115], v[176:179], v[184:187], v[112:115]
	v_mfma_f32_16x16x32_bf16 v[100:103], v[168:171], v[192:195], v[100:103]
	v_mfma_f32_16x16x32_bf16 v[96:99], v[176:179], v[192:195], v[96:99]
	v_mfma_f32_16x16x32_bf16 v[84:87], v[168:171], v[222:225], v[84:87]
	v_mfma_f32_16x16x32_bf16 v[80:83], v[176:179], v[222:225], v[80:83]
	v_mfma_f32_16x16x32_bf16 v[68:71], v[168:171], v[230:233], v[68:71]
	v_mfma_f32_16x16x32_bf16 v[64:67], v[176:179], v[230:233], v[64:67]
	v_mfma_f32_16x16x32_bf16 v[116:119], v[172:175], v[188:191], v[116:119]
	v_mfma_f32_16x16x32_bf16 v[112:115], v[180:183], v[188:191], v[112:115]
	v_mfma_f32_16x16x32_bf16 v[100:103], v[172:175], v[196:199], v[100:103]
	v_mfma_f32_16x16x32_bf16 v[96:99], v[180:183], v[196:199], v[96:99]
	v_mfma_f32_16x16x32_bf16 v[84:87], v[172:175], v[226:229], v[84:87]
	v_mfma_f32_16x16x32_bf16 v[80:83], v[180:183], v[226:229], v[80:83]
	v_mfma_f32_16x16x32_bf16 v[68:71], v[172:175], v[234:237], v[68:71]
	v_mfma_f32_16x16x32_bf16 v[64:67], v[180:183], v[234:237], v[64:67]
	s_setprio 0
	s_barrier
	s_add_i32 s52, s88, s59
	s_mov_b32 m0, s52
	ds_read_b128 v[184:187], v149 offset:49152
	ds_read_b128 v[188:191], v149 offset:50176
	ds_read_b128 v[192:195], v149 offset:51200
	ds_read_b128 v[196:199], v149 offset:52224
	ds_read_b128 v[222:225], v149 offset:53248
	ds_read_b128 v[226:229], v149 offset:54272
	ds_read_b128 v[230:233], v149 offset:55296
	ds_read_b128 v[234:237], v149 offset:56320
	s_add_u32 s4, s4, 0x80
	s_addc_u32 s5, s5, 0
	global_load_lds_dwordx4 v130, s[4:5]
	s_add_i32 m0, s52, 0x2000
	s_add_i32 s52, s89, s59
	global_load_lds_dwordx4 v134, s[4:5]
	s_add_u32 s4, s4, 0x40000
	s_addc_u32 s5, s5, 0
	s_mov_b32 m0, s52
	s_nop 0
	global_load_lds_dwordx4 v130, s[4:5]
	s_add_i32 m0, s52, 0x2000
	s_nop 0
	global_load_lds_dwordx4 v134, s[4:5]
	s_mov_b32 m0, s84
	s_nop 0
	global_load_lds_dwordx4 v128, s[98:99]
	s_mov_b32 m0, s85
	s_nop 0
	global_load_lds_dwordx4 v132, s[98:99]
	s_waitcnt vmcnt(8)
	s_waitcnt lgkmcnt(0)
	s_barrier
	s_setprio 1
	s_waitcnt lgkmcnt(0)
	v_mfma_f32_16x16x32_bf16 v[60:63], v[140:143], v[184:187], v[60:63]
	v_mfma_f32_16x16x32_bf16 v[56:59], v[154:157], v[184:187], v[56:59]
	v_mfma_f32_16x16x32_bf16 v[44:47], v[140:143], v[192:195], v[44:47]
	v_mfma_f32_16x16x32_bf16 v[40:43], v[154:157], v[192:195], v[40:43]
	v_mfma_f32_16x16x32_bf16 v[28:31], v[140:143], v[222:225], v[28:31]
	v_mfma_f32_16x16x32_bf16 v[24:27], v[154:157], v[222:225], v[24:27]
	v_mfma_f32_16x16x32_bf16 v[12:15], v[140:143], v[230:233], v[12:15]
	v_mfma_f32_16x16x32_bf16 v[8:11], v[154:157], v[230:233], v[8:11]
	v_mfma_f32_16x16x32_bf16 v[60:63], v[150:153], v[188:191], v[60:63]
	v_mfma_f32_16x16x32_bf16 v[56:59], v[164:167], v[188:191], v[56:59]
	v_mfma_f32_16x16x32_bf16 v[44:47], v[150:153], v[196:199], v[44:47]
	v_mfma_f32_16x16x32_bf16 v[40:43], v[164:167], v[196:199], v[40:43]
	v_mfma_f32_16x16x32_bf16 v[28:31], v[150:153], v[226:229], v[28:31]
	v_mfma_f32_16x16x32_bf16 v[24:27], v[164:167], v[226:229], v[24:27]
	v_mfma_f32_16x16x32_bf16 v[12:15], v[150:153], v[234:237], v[12:15]
	v_mfma_f32_16x16x32_bf16 v[8:11], v[164:167], v[234:237], v[8:11]
	v_mfma_f32_16x16x32_bf16 v[52:55], v[168:171], v[184:187], v[52:55]
	v_mfma_f32_16x16x32_bf16 v[48:51], v[176:179], v[184:187], v[48:51]
	v_mfma_f32_16x16x32_bf16 v[36:39], v[168:171], v[192:195], v[36:39]
	v_mfma_f32_16x16x32_bf16 v[32:35], v[176:179], v[192:195], v[32:35]
	v_mfma_f32_16x16x32_bf16 v[20:23], v[168:171], v[222:225], v[20:23]
	v_mfma_f32_16x16x32_bf16 v[16:19], v[176:179], v[222:225], v[16:19]
	v_mfma_f32_16x16x32_bf16 v[4:7], v[168:171], v[230:233], v[4:7]
	v_mfma_f32_16x16x32_bf16 v[0:3], v[176:179], v[230:233], v[0:3]
	v_mfma_f32_16x16x32_bf16 v[52:55], v[172:175], v[188:191], v[52:55]
	v_mfma_f32_16x16x32_bf16 v[48:51], v[180:183], v[188:191], v[48:51]
	v_mfma_f32_16x16x32_bf16 v[36:39], v[172:175], v[196:199], v[36:39]
	v_mfma_f32_16x16x32_bf16 v[32:35], v[180:183], v[196:199], v[32:35]
	v_mfma_f32_16x16x32_bf16 v[20:23], v[172:175], v[226:229], v[20:23]
	v_mfma_f32_16x16x32_bf16 v[16:19], v[180:183], v[226:229], v[16:19]
	v_mfma_f32_16x16x32_bf16 v[4:7], v[172:175], v[234:237], v[4:7]
	v_mfma_f32_16x16x32_bf16 v[0:3], v[180:183], v[234:237], v[0:3]
	s_setprio 0
	s_barrier
	s_add_i32 s87, s87, 2
	s_add_u32 s82, s82, 0x100
	s_addc_u32 s83, s83, 0
	s_add_u32 s29, s29, 0x100
	s_addc_u32 s43, s43, 0
	s_cmp_gt_u32 s87, 13
	s_cbranch_scc0 .LBB0_86
	s_and_b64 vcc, exec, s[12:13]
	s_cbranch_vccz .LBB0_89
	s_barrier

; #define PG8_STAGE(bufoff, gbase, voff) do { _Pragma("unroll") for (int _i = 0; _i < 2; ++_i) \
;         __builtin_amdgcn_global_load_lds((const unsigned*)((const char*)(gbase) + (voff)[_i]), (PG8_LAS unsigned*)(lds + (bufoff) + ldsw + _i * 8192), 16, 0, 0); } while (0)
; #define PG8_LDA(dst, b, h) do { _Pragma("unroll") for (int m = 0; m < 4; ++m) _Pragma("unroll") for (int k = 0; k < 2; ++k) dst[m][k] = *(const PG8_LAS bf16x8*)(lds + PG8_SA(b, h) + aoff + m * 2048 + k * 1024); } while (0)
; #define PG8_LDB(dst, b, h) do { _Pragma("unroll") for (int n = 0; n < 2; ++n) _Pragma("unroll") for (int k = 0; k < 2; ++k) dst[n][k] = *(const PG8_LAS bf16x8*)(lds + PG8_SB(b, h) + boff + n * 2048 + k * 1024); } while (0)
; #define PG8_MMA(ai, bj, At, Bt) do { __builtin_amdgcn_s_setprio(1); _Pragma("unroll") for (int m = 0; m < 4; ++m) _Pragma("unroll") for (int n = 0; n < 2; ++n) _Pragma("unroll") for (int k = 0; k < 2; ++k) \
;         acc[ai][bj][m][n] = __builtin_amdgcn_mfma_f32_16x16x32_bf16(Bt[n][k], At[m][k], acc[ai][bj][m][n], 0, 0, 0); __builtin_amdgcn_s_setprio(0); } while (0)
; #define PG8_WAIT_V(n) asm volatile("s_waitcnt vmcnt(" #n ")" ::: "memory")
; #define PG8_WAIT_L(n) asm volatile("s_waitcnt lgkmcnt(" #n ")" ::: "memory")
; template <class Epi, class Sched, bool ALIGN_EPI = false, bool SP2 = false>
; __device__ __forceinline__ void gemm_phase(PG8_LAS unsigned char* lds, const Gemm g, const Sched& S, const Epi& E) {
;     ...
;             const bool last = (t == nt - 2);
;             const char* a1 = cA + (size_t)(t + 1) * kstep;
;             const char* a2 = last ? nA : cA + (size_t)(t + 2) * kstep; const char* b2 = last ? nB : cB + (size_t)(t + 2) * kstep;
;             const char* a3 = a2 + kstep; const char* b3 = b2 + kstep;
;             if (last && has_next) S.a_ready(nxt);
;             if constexpr (SP2) {
;             PG8_LDB(B0, 0, 0); PG8_LDB(B1, 0, 1); PG8_SCHED; PG8_LDA(At, 0, 0); PG8_STAGE(PG8_SA(1, 1), a1 + hstep, voffA);
;             PG8_WAIT_V(8); PG8_WAIT_L(0); PG8_BAR; PG8_MMA(0, 0, At, B0); PG8_MMA(0, 1, At, B1); PG8_BAR; PG8_SCHED;
;             PG8_LDA(At, 0, 1); PG8_STAGE(PG8_SB(0, 0), b2, voffB); PG8_STAGE(PG8_SB(0, 1), b2 + hstep, voffB); PG8_STAGE(PG8_SA(0, 0), a2, voffA);
;             PG8_WAIT_V(8); PG8_WAIT_L(0); PG8_BAR; PG8_MMA(1, 0, At, B0); PG8_MMA(1, 1, At, B1); PG8_BAR; PG8_SCHED;
.LBB0_322:
	s_add_i32 s56, 0, 0x10000
	s_add_i32 vcc_lo, 0, 0x14000
	s_waitcnt lgkmcnt(0)
	ds_read_b128 v[154:157], v246
	ds_read_b128 v[164:167], v246 offset:1024
	ds_read_b128 v[168:171], v246 offset:2048
	ds_read_b128 v[172:175], v246 offset:3072
	ds_read_b128 v[176:179], v246 offset:16384
	ds_read_b128 v[180:183], v246 offset:17408
	ds_read_b128 v[184:187], v246 offset:18432
	ds_read_b128 v[188:191], v246 offset:19456
	s_add_i32 m0, s89, 0xc000
	ds_read_b128 v[192:195], v145
	ds_read_b128 v[196:199], v145 offset:1024
	ds_read_b128 v[222:225], v145 offset:2048
	ds_read_b128 v[226:229], v145 offset:3072
	ds_read_b128 v[230:233], v145 offset:4096
	ds_read_b128 v[234:237], v145 offset:5120
	ds_read_b128 v[238:241], v145 offset:6144
	ds_read_b128 v[242:245], v145 offset:7168
	global_load_lds_dwordx4 v150, s[14:15]
	s_add_i32 m0, s89, 0xe000
	s_nop 0
	global_load_lds_dwordx4 v152, s[14:15]
	s_add_u32 s4, s14, 0xfff80080
	s_addc_u32 s5, s15, -1
	s_cmp_eq_u32 s55, 28
	s_cselect_b32 s53, s1, s5
	s_cselect_b32 s52, s28, s4
	s_cselect_b32 s5, s29, s54
	s_cselect_b32 s4, s43, s45
	s_waitcnt vmcnt(8)
	s_waitcnt lgkmcnt(0)
	s_barrier
	s_setprio 1
	s_waitcnt lgkmcnt(0)
	v_mfma_f32_16x16x32_bf16 v[124:127], v[154:157], v[192:195], v[124:127]
	v_mfma_f32_16x16x32_bf16 v[120:123], v[168:171], v[192:195], v[120:123]
	v_mfma_f32_16x16x32_bf16 v[116:119], v[154:157], v[222:225], v[116:119]
	v_mfma_f32_16x16x32_bf16 v[112:115], v[168:171], v[222:225], v[112:115]
	v_mfma_f32_16x16x32_bf16 v[108:111], v[154:157], v[230:233], v[108:111]
	v_mfma_f32_16x16x32_bf16 v[104:107], v[168:171], v[230:233], v[104:107]
	v_mfma_f32_16x16x32_bf16 v[100:103], v[154:157], v[238:241], v[100:103]
	v_mfma_f32_16x16x32_bf16 v[96:99], v[168:171], v[238:241], v[96:99]
	v_mfma_f32_16x16x32_bf16 v[124:127], v[164:167], v[196:199], v[124:127]
	v_mfma_f32_16x16x32_bf16 v[120:123], v[172:175], v[196:199], v[120:123]
	v_mfma_f32_16x16x32_bf16 v[116:119], v[164:167], v[226:229], v[116:119]
	v_mfma_f32_16x16x32_bf16 v[112:115], v[172:175], v[226:229], v[112:115]
	v_mfma_f32_16x16x32_bf16 v[108:111], v[164:167], v[234:237], v[108:111]
	v_mfma_f32_16x16x32_bf16 v[104:107], v[172:175], v[234:237], v[104:107]
	v_mfma_f32_16x16x32_bf16 v[100:103], v[164:167], v[242:245], v[100:103]
	v_mfma_f32_16x16x32_bf16 v[96:99], v[172:175], v[242:245], v[96:99]
	v_mfma_f32_16x16x32_bf16 v[92:95], v[176:179], v[192:195], v[92:95]
	v_mfma_f32_16x16x32_bf16 v[88:91], v[184:187], v[192:195], v[88:91]
	v_mfma_f32_16x16x32_bf16 v[84:87], v[176:179], v[222:225], v[84:87]
	v_mfma_f32_16x16x32_bf16 v[80:83], v[184:187], v[222:225], v[80:83]
	v_mfma_f32_16x16x32_bf16 v[76:79], v[176:179], v[230:233], v[76:79]
	v_mfma_f32_16x16x32_bf16 v[72:75], v[184:187], v[230:233], v[72:75]
	v_mfma_f32_16x16x32_bf16 v[68:71], v[176:179], v[238:241], v[68:71]
	v_mfma_f32_16x16x32_bf16 v[64:67], v[184:187], v[238:241], v[64:67]
	v_mfma_f32_16x16x32_bf16 v[92:95], v[180:183], v[196:199], v[92:95]
	v_mfma_f32_16x16x32_bf16 v[88:91], v[188:191], v[196:199], v[88:91]
	v_mfma_f32_16x16x32_bf16 v[84:87], v[180:183], v[226:229], v[84:87]
	v_mfma_f32_16x16x32_bf16 v[80:83], v[188:191], v[226:229], v[80:83]
	v_mfma_f32_16x16x32_bf16 v[76:79], v[180:183], v[234:237], v[76:79]
	v_mfma_f32_16x16x32_bf16 v[72:75], v[188:191], v[234:237], v[72:75]
	v_mfma_f32_16x16x32_bf16 v[68:71], v[180:183], v[242:245], v[68:71]
	v_mfma_f32_16x16x32_bf16 v[64:67], v[188:191], v[242:245], v[64:67]
	s_setprio 0
	s_barrier
	s_add_i32 s56, s56, s63
	s_mov_b32 m0, s56
	ds_read_b128 v[192:195], v145 offset:16384
	ds_read_b128 v[196:199], v145 offset:17408
	ds_read_b128 v[222:225], v145 offset:18432
	ds_read_b128 v[226:229], v145 offset:19456
	ds_read_b128 v[230:233], v145 offset:20480
	ds_read_b128 v[234:237], v145 offset:21504
	ds_read_b128 v[238:241], v145 offset:22528
	ds_read_b128 v[242:245], v145 offset:23552
	global_load_lds_dwordx4 v130, s[4:5]
	s_add_i32 m0, s56, 0x2000
	s_add_u32 s56, s4, 0x80000
	s_addc_u32 s57, s5, 0
	s_add_i32 vcc_lo, vcc_lo, s63
	global_load_lds_dwordx4 v134, s[4:5]
	s_mov_b32 m0, vcc_lo
	s_nop 0
	global_load_lds_dwordx4 v130, s[56:57]
	s_add_i32 m0, vcc_lo, 0x2000
	s_nop 0
	global_load_lds_dwordx4 v134, s[56:57]
	s_mov_b32 m0, s89
	s_nop 0
	global_load_lds_dwordx4 v128, s[52:53]
	s_mov_b32 m0, s91
	s_nop 0
	global_load_lds_dwordx4 v132, s[52:53]
	s_add_u32 s98, s52, 0x80
	s_addc_u32 s99, s53, 0
	s_waitcnt vmcnt(8)
	s_waitcnt lgkmcnt(0)
	s_barrier
	s_setprio 1
	s_waitcnt lgkmcnt(0)
	v_mfma_f32_16x16x32_bf16 v[60:63], v[154:157], v[192:195], v[60:63]
	v_mfma_f32_16x16x32_bf16 v[56:59], v[168:171], v[192:195], v[56:59]
	v_mfma_f32_16x16x32_bf16 v[52:55], v[154:157], v[222:225], v[52:55]
	v_mfma_f32_16x16x32_bf16 v[48:51], v[168:171], v[222:225], v[48:51]
	v_mfma_f32_16x16x32_bf16 v[44:47], v[154:157], v[230:233], v[44:47]
	v_mfma_f32_16x16x32_bf16 v[40:43], v[168:171], v[230:233], v[40:43]
	v_mfma_f32_16x16x32_bf16 v[36:39], v[154:157], v[238:241], v[36:39]
	v_mfma_f32_16x16x32_bf16 v[32:35], v[168:171], v[238:241], v[32:35]
	v_mfma_f32_16x16x32_bf16 v[60:63], v[164:167], v[196:199], v[60:63]
	v_mfma_f32_16x16x32_bf16 v[56:59], v[172:175], v[196:199], v[56:59]
	v_mfma_f32_16x16x32_bf16 v[52:55], v[164:167], v[226:229], v[52:55]
	v_mfma_f32_16x16x32_bf16 v[48:51], v[172:175], v[226:229], v[48:51]
	v_mfma_f32_16x16x32_bf16 v[44:47], v[164:167], v[234:237], v[44:47]
	v_mfma_f32_16x16x32_bf16 v[40:43], v[172:175], v[234:237], v[40:43]
	v_mfma_f32_16x16x32_bf16 v[36:39], v[164:167], v[242:245], v[36:39]
	v_mfma_f32_16x16x32_bf16 v[32:35], v[172:175], v[242:245], v[32:35]
	v_mfma_f32_16x16x32_bf16 v[28:31], v[176:179], v[192:195], v[28:31]
	v_mfma_f32_16x16x32_bf16 v[24:27], v[184:187], v[192:195], v[24:27]
	v_mfma_f32_16x16x32_bf16 v[20:23], v[176:179], v[222:225], v[20:23]
	v_mfma_f32_16x16x32_bf16 v[16:19], v[184:187], v[222:225], v[16:19]
	v_mfma_f32_16x16x32_bf16 v[12:15], v[176:179], v[230:233], v[12:15]
	v_mfma_f32_16x16x32_bf16 v[8:11], v[184:187], v[230:233], v[8:11]
	v_mfma_f32_16x16x32_bf16 v[4:7], v[176:179], v[238:241], v[4:7]
	v_mfma_f32_16x16x32_bf16 v[0:3], v[184:187], v[238:241], v[0:3]
	v_mfma_f32_16x16x32_bf16 v[28:31], v[180:183], v[196:199], v[28:31]
	v_mfma_f32_16x16x32_bf16 v[24:27], v[188:191], v[196:199], v[24:27]
	v_mfma_f32_16x16x32_bf16 v[20:23], v[180:183], v[226:229], v[20:23]
	v_mfma_f32_16x16x32_bf16 v[16:19], v[188:191], v[226:229], v[16:19]
	v_mfma_f32_16x16x32_bf16 v[12:15], v[180:183], v[234:237], v[12:15]
	v_mfma_f32_16x16x32_bf16 v[8:11], v[188:191], v[234:237], v[8:11]
	v_mfma_f32_16x16x32_bf16 v[4:7], v[180:183], v[242:245], v[4:7]
	v_mfma_f32_16x16x32_bf16 v[0:3], v[188:191], v[242:245], v[0:3]
	s_setprio 0
	s_barrier
; #define PG8_STAGE(bufoff, gbase, voff) do { _Pragma("unroll") for (int _i = 0; _i < 2; ++_i) \
;         __builtin_amdgcn_global_load_lds((const unsigned*)((const char*)(gbase) + (voff)[_i]), (PG8_LAS unsigned*)(lds + (bufoff) + ldsw + _i * 8192), 16, 0, 0); } while (0)
; #define PG8_LDA(dst, b, h) do { _Pragma("unroll") for (int m = 0; m < 4; ++m) _Pragma("unroll") for (int k = 0; k < 2; ++k) dst[m][k] = *(const PG8_LAS bf16x8*)(lds + PG8_SA(b, h) + aoff + m * 2048 + k * 1024); } while (0)
; #define PG8_LDB(dst, b, h) do { _Pragma("unroll") for (int n = 0; n < 2; ++n) _Pragma("unroll") for (int k = 0; k < 2; ++k) dst[n][k] = *(const PG8_LAS bf16x8*)(lds + PG8_SB(b, h) + boff + n * 2048 + k * 1024); } while (0)
; #define PG8_MMA(ai, bj, At, Bt) do { __builtin_amdgcn_s_setprio(1); _Pragma("unroll") for (int m = 0; m < 4; ++m) _Pragma("unroll") for (int n = 0; n < 2; ++n) _Pragma("unroll") for (int k = 0; k < 2; ++k) \
;         acc[ai][bj][m][n] = __builtin_amdgcn_mfma_f32_16x16x32_bf16(Bt[n][k], At[m][k], acc[ai][bj][m][n], 0, 0, 0); __builtin_amdgcn_s_setprio(0); } while (0)
; #define PG8_WAIT_V(n) asm volatile("s_waitcnt vmcnt(" #n ")" ::: "memory")
; #define PG8_WAIT_L(n) asm volatile("s_waitcnt lgkmcnt(" #n ")" ::: "memory")
; #define PG8_BAR __builtin_amdgcn_s_barrier()
; #define PG8_SCHED __builtin_amdgcn_sched_barrier(0)
; template <class Epi, class Sched, bool ALIGN_EPI = false, bool SP2 = false>
; __device__ __forceinline__ void gemm_phase(PG8_LAS unsigned char* lds, const Gemm g, const Sched& S, const Epi& E) {
;     ...
;             PG8_LDB(B0, 1, 0); PG8_LDB(B1, 1, 1); PG8_SCHED; PG8_LDA(At, 1, 0); PG8_STAGE(PG8_SA(0, 1), a2 + hstep, voffA);
;             PG8_WAIT_V(8); PG8_WAIT_L(0); PG8_BAR; PG8_MMA(0, 0, At, B0); PG8_MMA(0, 1, At, B1); PG8_BAR; PG8_SCHED;
;             PG8_LDA(At, 1, 1); PG8_STAGE(PG8_SB(1, 0), b3, voffB); PG8_STAGE(PG8_SB(1, 1), b3 + hstep, voffB); PG8_STAGE(PG8_SA(1, 0), a3, voffA);
;             PG8_WAIT_V(8); PG8_WAIT_L(0); PG8_BAR; PG8_MMA(1, 0, At, B0); PG8_MMA(1, 1, At, B1); PG8_BAR; PG8_SCHED;
;     ...
;         if constexpr (ALIGN_EPI) { if (wr == 0) PG8_BAR; }
	s_add_i32 s56, 0, 0x18000
	s_add_i32 s57, 0, 0x1c000
	ds_read_b128 v[154:157], v246 offset:32768
	ds_read_b128 v[164:167], v246 offset:33792
	ds_read_b128 v[168:171], v246 offset:34816
	ds_read_b128 v[172:175], v246 offset:35840
	ds_read_b128 v[176:179], v246 offset:49152
	ds_read_b128 v[180:183], v246 offset:50176
	ds_read_b128 v[184:187], v246 offset:51200
	ds_read_b128 v[188:191], v246 offset:52224
	s_add_u32 s52, s52, 0x80000
	s_addc_u32 s53, s53, 0
	s_mov_b32 m0, s12
	ds_read_b128 v[192:195], v145 offset:32768
	ds_read_b128 v[196:199], v145 offset:33792
	ds_read_b128 v[222:225], v145 offset:34816
	ds_read_b128 v[226:229], v145 offset:35840
	ds_read_b128 v[230:233], v145 offset:36864
	ds_read_b128 v[234:237], v145 offset:37888
	ds_read_b128 v[238:241], v145 offset:38912
	ds_read_b128 v[242:245], v145 offset:39936
	global_load_lds_dwordx4 v128, s[52:53]
	s_mov_b32 m0, s13
	s_nop 0
	global_load_lds_dwordx4 v132, s[52:53]
	s_waitcnt vmcnt(8)
	s_waitcnt lgkmcnt(0)
	s_barrier
	s_setprio 1
	s_waitcnt lgkmcnt(0)
	v_mfma_f32_16x16x32_bf16 v[124:127], v[154:157], v[192:195], v[124:127]
	v_mfma_f32_16x16x32_bf16 v[120:123], v[168:171], v[192:195], v[120:123]
	v_mfma_f32_16x16x32_bf16 v[116:119], v[154:157], v[222:225], v[116:119]
	v_mfma_f32_16x16x32_bf16 v[112:115], v[168:171], v[222:225], v[112:115]
	v_mfma_f32_16x16x32_bf16 v[108:111], v[154:157], v[230:233], v[108:111]
	v_mfma_f32_16x16x32_bf16 v[104:107], v[168:171], v[230:233], v[104:107]
	v_mfma_f32_16x16x32_bf16 v[100:103], v[154:157], v[238:241], v[100:103]
	v_mfma_f32_16x16x32_bf16 v[96:99], v[168:171], v[238:241], v[96:99]
	v_mfma_f32_16x16x32_bf16 v[124:127], v[164:167], v[196:199], v[124:127]
	v_mfma_f32_16x16x32_bf16 v[120:123], v[172:175], v[196:199], v[120:123]
	v_mfma_f32_16x16x32_bf16 v[116:119], v[164:167], v[226:229], v[116:119]
	v_mfma_f32_16x16x32_bf16 v[112:115], v[172:175], v[226:229], v[112:115]
	v_mfma_f32_16x16x32_bf16 v[108:111], v[164:167], v[234:237], v[108:111]
	v_mfma_f32_16x16x32_bf16 v[104:107], v[172:175], v[234:237], v[104:107]
	v_mfma_f32_16x16x32_bf16 v[100:103], v[164:167], v[242:245], v[100:103]
	v_mfma_f32_16x16x32_bf16 v[96:99], v[172:175], v[242:245], v[96:99]
	v_mfma_f32_16x16x32_bf16 v[92:95], v[176:179], v[192:195], v[92:95]
	v_mfma_f32_16x16x32_bf16 v[88:91], v[184:187], v[192:195], v[88:91]
	v_mfma_f32_16x16x32_bf16 v[84:87], v[176:179], v[222:225], v[84:87]
	v_mfma_f32_16x16x32_bf16 v[80:83], v[184:187], v[222:225], v[80:83]
	v_mfma_f32_16x16x32_bf16 v[76:79], v[176:179], v[230:233], v[76:79]
	v_mfma_f32_16x16x32_bf16 v[72:75], v[184:187], v[230:233], v[72:75]
	v_mfma_f32_16x16x32_bf16 v[68:71], v[176:179], v[238:241], v[68:71]
	v_mfma_f32_16x16x32_bf16 v[64:67], v[184:187], v[238:241], v[64:67]
	v_mfma_f32_16x16x32_bf16 v[92:95], v[180:183], v[196:199], v[92:95]
	v_mfma_f32_16x16x32_bf16 v[88:91], v[188:191], v[196:199], v[88:91]
	v_mfma_f32_16x16x32_bf16 v[84:87], v[180:183], v[226:229], v[84:87]
	v_mfma_f32_16x16x32_bf16 v[80:83], v[188:191], v[226:229], v[80:83]
	v_mfma_f32_16x16x32_bf16 v[76:79], v[180:183], v[234:237], v[76:79]
	v_mfma_f32_16x16x32_bf16 v[72:75], v[188:191], v[234:237], v[72:75]
	v_mfma_f32_16x16x32_bf16 v[68:71], v[180:183], v[242:245], v[68:71]
	v_mfma_f32_16x16x32_bf16 v[64:67], v[188:191], v[242:245], v[64:67]
	s_setprio 0
	s_barrier
	s_add_i32 s52, s56, s63
	s_mov_b32 m0, s52
	ds_read_b128 v[192:195], v145 offset:49152
	ds_read_b128 v[196:199], v145 offset:50176
	ds_read_b128 v[222:225], v145 offset:51200
	ds_read_b128 v[226:229], v145 offset:52224
	ds_read_b128 v[230:233], v145 offset:53248
	ds_read_b128 v[234:237], v145 offset:54272
	ds_read_b128 v[238:241], v145 offset:55296
	ds_read_b128 v[242:245], v145 offset:56320
	s_add_u32 s4, s4, 0x80
	s_addc_u32 s5, s5, 0
	global_load_lds_dwordx4 v130, s[4:5]
	s_add_i32 m0, s52, 0x2000
	s_add_i32 s52, s57, s63
	global_load_lds_dwordx4 v134, s[4:5]
	s_add_u32 s4, s4, 0x80000
	s_addc_u32 s5, s5, 0
	s_mov_b32 m0, s52
	s_nop 0
	global_load_lds_dwordx4 v130, s[4:5]
	s_add_i32 m0, s52, 0x2000
	s_nop 0
	global_load_lds_dwordx4 v134, s[4:5]
	s_mov_b32 m0, s78
	s_nop 0
	global_load_lds_dwordx4 v128, s[98:99]
	s_mov_b32 m0, s79
	s_nop 0
	global_load_lds_dwordx4 v132, s[98:99]
	s_waitcnt vmcnt(8)
	s_waitcnt lgkmcnt(0)
	s_barrier
	s_setprio 1
	s_waitcnt lgkmcnt(0)
	v_mfma_f32_16x16x32_bf16 v[60:63], v[154:157], v[192:195], v[60:63]
	v_mfma_f32_16x16x32_bf16 v[56:59], v[168:171], v[192:195], v[56:59]
	v_mfma_f32_16x16x32_bf16 v[52:55], v[154:157], v[222:225], v[52:55]
	v_mfma_f32_16x16x32_bf16 v[48:51], v[168:171], v[222:225], v[48:51]
	v_mfma_f32_16x16x32_bf16 v[44:47], v[154:157], v[230:233], v[44:47]
	v_mfma_f32_16x16x32_bf16 v[40:43], v[168:171], v[230:233], v[40:43]
	v_mfma_f32_16x16x32_bf16 v[36:39], v[154:157], v[238:241], v[36:39]
	v_mfma_f32_16x16x32_bf16 v[32:35], v[168:171], v[238:241], v[32:35]
	v_mfma_f32_16x16x32_bf16 v[60:63], v[164:167], v[196:199], v[60:63]
	v_mfma_f32_16x16x32_bf16 v[56:59], v[172:175], v[196:199], v[56:59]
	v_mfma_f32_16x16x32_bf16 v[52:55], v[164:167], v[226:229], v[52:55]
	v_mfma_f32_16x16x32_bf16 v[48:51], v[172:175], v[226:229], v[48:51]
	v_mfma_f32_16x16x32_bf16 v[44:47], v[164:167], v[234:237], v[44:47]
	v_mfma_f32_16x16x32_bf16 v[40:43], v[172:175], v[234:237], v[40:43]
	v_mfma_f32_16x16x32_bf16 v[36:39], v[164:167], v[242:245], v[36:39]
	v_mfma_f32_16x16x32_bf16 v[32:35], v[172:175], v[242:245], v[32:35]
	v_mfma_f32_16x16x32_bf16 v[28:31], v[176:179], v[192:195], v[28:31]
	v_mfma_f32_16x16x32_bf16 v[24:27], v[184:187], v[192:195], v[24:27]
	v_mfma_f32_16x16x32_bf16 v[20:23], v[176:179], v[222:225], v[20:23]
	v_mfma_f32_16x16x32_bf16 v[16:19], v[184:187], v[222:225], v[16:19]
	v_mfma_f32_16x16x32_bf16 v[12:15], v[176:179], v[230:233], v[12:15]
	v_mfma_f32_16x16x32_bf16 v[8:11], v[184:187], v[230:233], v[8:11]
	v_mfma_f32_16x16x32_bf16 v[4:7], v[176:179], v[238:241], v[4:7]
	v_mfma_f32_16x16x32_bf16 v[0:3], v[184:187], v[238:241], v[0:3]
	v_mfma_f32_16x16x32_bf16 v[28:31], v[180:183], v[196:199], v[28:31]
	v_mfma_f32_16x16x32_bf16 v[24:27], v[188:191], v[196:199], v[24:27]
	v_mfma_f32_16x16x32_bf16 v[20:23], v[180:183], v[226:229], v[20:23]
	v_mfma_f32_16x16x32_bf16 v[16:19], v[188:191], v[226:229], v[16:19]
	v_mfma_f32_16x16x32_bf16 v[12:15], v[180:183], v[234:237], v[12:15]
	v_mfma_f32_16x16x32_bf16 v[8:11], v[188:191], v[234:237], v[8:11]
	v_mfma_f32_16x16x32_bf16 v[4:7], v[180:183], v[242:245], v[4:7]
	v_mfma_f32_16x16x32_bf16 v[0:3], v[188:191], v[242:245], v[0:3]
	s_setprio 0
	s_barrier
	s_add_i32 s55, s55, 2
	s_add_u32 s14, s14, 0x100
	s_addc_u32 s15, s15, 0
	s_add_u32 s45, s45, 0x100
	s_addc_u32 s54, s54, 0
	s_cmp_gt_u32 s55, 29
	s_cbranch_scc0 .LBB0_322
	s_and_b64 vcc, exec, s[82:83]
	s_cbranch_vccz .LBB0_325
	s_barrier

; #define PG8_STAGE(bufoff, gbase, voff) do { _Pragma("unroll") for (int _i = 0; _i < 2; ++_i) \
;         __builtin_amdgcn_global_load_lds((const unsigned*)((const char*)(gbase) + (voff)[_i]), (PG8_LAS unsigned*)(lds + (bufoff) + ldsw + _i * 8192), 16, 0, 0); } while (0)
; #define PG8_LDA(dst, b, h) do { _Pragma("unroll") for (int m = 0; m < 4; ++m) _Pragma("unroll") for (int k = 0; k < 2; ++k) dst[m][k] = *(const PG8_LAS bf16x8*)(lds + PG8_SA(b, h) + aoff + m * 2048 + k * 1024); } while (0)
; #define PG8_LDB(dst, b, h) do { _Pragma("unroll") for (int n = 0; n < 2; ++n) _Pragma("unroll") for (int k = 0; k < 2; ++k) dst[n][k] = *(const PG8_LAS bf16x8*)(lds + PG8_SB(b, h) + boff + n * 2048 + k * 1024); } while (0)
; #define PG8_MMA(ai, bj, At, Bt) do { __builtin_amdgcn_s_setprio(1); _Pragma("unroll") for (int m = 0; m < 4; ++m) _Pragma("unroll") for (int n = 0; n < 2; ++n) _Pragma("unroll") for (int k = 0; k < 2; ++k) \
;         acc[ai][bj][m][n] = __builtin_amdgcn_mfma_f32_16x16x32_bf16(Bt[n][k], At[m][k], acc[ai][bj][m][n], 0, 0, 0); __builtin_amdgcn_s_setprio(0); } while (0)
; #define PG8_WAIT_V(n) asm volatile("s_waitcnt vmcnt(" #n ")" ::: "memory")
; #define PG8_WAIT_L(n) asm volatile("s_waitcnt lgkmcnt(" #n ")" ::: "memory")
; template <class Epi, class Sched, bool ALIGN_EPI = false, bool SP2 = false>
; __device__ __forceinline__ void gemm_phase(PG8_LAS unsigned char* lds, const Gemm g, const Sched& S, const Epi& E) {
;     ...
;             const bool last = (t == nt - 2);
;             const char* a1 = cA + (size_t)(t + 1) * kstep;
;             const char* a2 = last ? nA : cA + (size_t)(t + 2) * kstep; const char* b2 = last ? nB : cB + (size_t)(t + 2) * kstep;
;             const char* a3 = a2 + kstep; const char* b3 = b2 + kstep;
;             if (last && has_next) S.a_ready(nxt);
;             if constexpr (SP2) {
;             PG8_LDB(B0, 0, 0); PG8_LDB(B1, 0, 1); PG8_SCHED; PG8_LDA(At, 0, 0); PG8_STAGE(PG8_SA(1, 1), a1 + hstep, voffA);
;             PG8_WAIT_V(8); PG8_WAIT_L(0); PG8_BAR; PG8_MMA(0, 0, At, B0); PG8_MMA(0, 1, At, B1); PG8_BAR; PG8_SCHED;
;             PG8_LDA(At, 0, 1); PG8_STAGE(PG8_SB(0, 0), b2, voffB); PG8_STAGE(PG8_SB(0, 1), b2 + hstep, voffB); PG8_STAGE(PG8_SA(0, 0), a2, voffA);
;             PG8_WAIT_V(8); PG8_WAIT_L(0); PG8_BAR; PG8_MMA(1, 0, At, B0); PG8_MMA(1, 1, At, B1); PG8_BAR; PG8_SCHED;
.LBB0_849:
	s_add_i32 s76, 0, 0x10000
	s_add_i32 s78, 0, 0x14000
	ds_read_b128 v[144:147], v200
	ds_read_b128 v[148:151], v200 offset:1024
	ds_read_b128 v[152:155], v200 offset:2048
	ds_read_b128 v[156:159], v200 offset:3072
	ds_read_b128 v[164:167], v200 offset:16384
	ds_read_b128 v[168:171], v200 offset:17408
	ds_read_b128 v[172:175], v200 offset:18432
	ds_read_b128 v[176:179], v200 offset:19456
	s_add_i32 m0, s51, 0xc000
	ds_read_b128 v[180:183], v143
	ds_read_b128 v[184:187], v143 offset:1024
	ds_read_b128 v[188:191], v143 offset:2048
	ds_read_b128 v[192:195], v143 offset:3072
	ds_read_b128 v[196:199], v143 offset:4096
	ds_read_b128 v[222:225], v143 offset:5120
	ds_read_b128 v[226:229], v143 offset:6144
	ds_read_b128 v[230:233], v143 offset:7168
	global_load_lds_dwordx4 v134, s[70:71]
	s_add_i32 m0, s51, 0xe000
	s_nop 0
	global_load_lds_dwordx4 v136, s[70:71]
	s_add_u32 s4, s70, 0xfff80080
	s_addc_u32 s5, s71, -1
	s_cmp_eq_u32 s75, 28
	s_cselect_b32 s53, s11, s5
	s_cselect_b32 s52, s63, s4
	s_cselect_b32 s5, s13, s74
	s_cselect_b32 s4, s72, s73
	s_waitcnt vmcnt(8)
	s_waitcnt lgkmcnt(0)
	s_barrier
	s_setprio 1
	s_waitcnt lgkmcnt(0)
	v_mfma_f32_16x16x32_bf16 v[124:127], v[144:147], v[180:183], v[124:127]
	v_mfma_f32_16x16x32_bf16 v[116:119], v[152:155], v[180:183], v[116:119]
	v_mfma_f32_16x16x32_bf16 v[108:111], v[144:147], v[188:191], v[108:111]
	v_mfma_f32_16x16x32_bf16 v[100:103], v[152:155], v[188:191], v[100:103]
	v_mfma_f32_16x16x32_bf16 v[92:95], v[144:147], v[196:199], v[92:95]
	v_mfma_f32_16x16x32_bf16 v[84:87], v[152:155], v[196:199], v[84:87]
	v_mfma_f32_16x16x32_bf16 v[76:79], v[144:147], v[226:229], v[76:79]
	v_mfma_f32_16x16x32_bf16 v[68:71], v[152:155], v[226:229], v[68:71]
	v_mfma_f32_16x16x32_bf16 v[124:127], v[148:151], v[184:187], v[124:127]
	v_mfma_f32_16x16x32_bf16 v[116:119], v[156:159], v[184:187], v[116:119]
	v_mfma_f32_16x16x32_bf16 v[108:111], v[148:151], v[192:195], v[108:111]
	v_mfma_f32_16x16x32_bf16 v[100:103], v[156:159], v[192:195], v[100:103]
	v_mfma_f32_16x16x32_bf16 v[92:95], v[148:151], v[222:225], v[92:95]
	v_mfma_f32_16x16x32_bf16 v[84:87], v[156:159], v[222:225], v[84:87]
	v_mfma_f32_16x16x32_bf16 v[76:79], v[148:151], v[230:233], v[76:79]
	v_mfma_f32_16x16x32_bf16 v[68:71], v[156:159], v[230:233], v[68:71]
	v_mfma_f32_16x16x32_bf16 v[120:123], v[164:167], v[180:183], v[120:123]
	v_mfma_f32_16x16x32_bf16 v[112:115], v[172:175], v[180:183], v[112:115]
	v_mfma_f32_16x16x32_bf16 v[104:107], v[164:167], v[188:191], v[104:107]
	v_mfma_f32_16x16x32_bf16 v[96:99], v[172:175], v[188:191], v[96:99]
	v_mfma_f32_16x16x32_bf16 v[88:91], v[164:167], v[196:199], v[88:91]
	v_mfma_f32_16x16x32_bf16 v[80:83], v[172:175], v[196:199], v[80:83]
	v_mfma_f32_16x16x32_bf16 v[72:75], v[164:167], v[226:229], v[72:75]
	v_mfma_f32_16x16x32_bf16 v[64:67], v[172:175], v[226:229], v[64:67]
	v_mfma_f32_16x16x32_bf16 v[120:123], v[168:171], v[184:187], v[120:123]
	v_mfma_f32_16x16x32_bf16 v[112:115], v[176:179], v[184:187], v[112:115]
	v_mfma_f32_16x16x32_bf16 v[104:107], v[168:171], v[192:195], v[104:107]
	v_mfma_f32_16x16x32_bf16 v[96:99], v[176:179], v[192:195], v[96:99]
	v_mfma_f32_16x16x32_bf16 v[88:91], v[168:171], v[222:225], v[88:91]
	v_mfma_f32_16x16x32_bf16 v[80:83], v[176:179], v[222:225], v[80:83]
	v_mfma_f32_16x16x32_bf16 v[72:75], v[168:171], v[230:233], v[72:75]
	v_mfma_f32_16x16x32_bf16 v[64:67], v[176:179], v[230:233], v[64:67]
	s_setprio 0
	s_barrier
	s_add_i32 s76, s76, s24
	s_mov_b32 m0, s76
	ds_read_b128 v[180:183], v143 offset:16384
	ds_read_b128 v[184:187], v143 offset:17408
	ds_read_b128 v[188:191], v143 offset:18432
	ds_read_b128 v[192:195], v143 offset:19456
	ds_read_b128 v[196:199], v143 offset:20480
	ds_read_b128 v[222:225], v143 offset:21504
	ds_read_b128 v[226:229], v143 offset:22528
	ds_read_b128 v[230:233], v143 offset:23552
	global_load_lds_dwordx4 v160, s[4:5]
	s_add_i32 m0, s76, 0x2000
	s_add_u32 s76, s4, 0x80000
	s_addc_u32 s77, s5, 0
	s_add_i32 s78, s78, s24
	global_load_lds_dwordx4 v128, s[4:5]
	s_mov_b32 m0, s78
	s_nop 0
	global_load_lds_dwordx4 v160, s[76:77]
	s_add_i32 m0, s78, 0x2000
	s_nop 0
	global_load_lds_dwordx4 v128, s[76:77]
	s_mov_b32 m0, s51
	s_nop 0
	global_load_lds_dwordx4 v132, s[52:53]
	s_mov_b32 m0, s55
	s_nop 0
	global_load_lds_dwordx4 v130, s[52:53]
	s_add_u32 s98, s52, 0x80
	s_addc_u32 s99, s53, 0
	s_waitcnt vmcnt(8)
	s_waitcnt lgkmcnt(0)
	s_barrier
	s_setprio 1
	s_waitcnt lgkmcnt(0)
	v_mfma_f32_16x16x32_bf16 v[60:63], v[144:147], v[180:183], v[60:63]
	v_mfma_f32_16x16x32_bf16 v[52:55], v[152:155], v[180:183], v[52:55]
	v_mfma_f32_16x16x32_bf16 v[44:47], v[144:147], v[188:191], v[44:47]
	v_mfma_f32_16x16x32_bf16 v[36:39], v[152:155], v[188:191], v[36:39]
	v_mfma_f32_16x16x32_bf16 v[28:31], v[144:147], v[196:199], v[28:31]
	v_mfma_f32_16x16x32_bf16 v[20:23], v[152:155], v[196:199], v[20:23]
	v_mfma_f32_16x16x32_bf16 v[12:15], v[144:147], v[226:229], v[12:15]
	v_mfma_f32_16x16x32_bf16 v[4:7], v[152:155], v[226:229], v[4:7]
	v_mfma_f32_16x16x32_bf16 v[60:63], v[148:151], v[184:187], v[60:63]
	v_mfma_f32_16x16x32_bf16 v[52:55], v[156:159], v[184:187], v[52:55]
	v_mfma_f32_16x16x32_bf16 v[44:47], v[148:151], v[192:195], v[44:47]
	v_mfma_f32_16x16x32_bf16 v[36:39], v[156:159], v[192:195], v[36:39]
	v_mfma_f32_16x16x32_bf16 v[28:31], v[148:151], v[222:225], v[28:31]
	v_mfma_f32_16x16x32_bf16 v[20:23], v[156:159], v[222:225], v[20:23]
	v_mfma_f32_16x16x32_bf16 v[12:15], v[148:151], v[230:233], v[12:15]
	v_mfma_f32_16x16x32_bf16 v[4:7], v[156:159], v[230:233], v[4:7]
	v_mfma_f32_16x16x32_bf16 v[56:59], v[164:167], v[180:183], v[56:59]
	v_mfma_f32_16x16x32_bf16 v[48:51], v[172:175], v[180:183], v[48:51]
	v_mfma_f32_16x16x32_bf16 v[40:43], v[164:167], v[188:191], v[40:43]
	v_mfma_f32_16x16x32_bf16 v[32:35], v[172:175], v[188:191], v[32:35]
	v_mfma_f32_16x16x32_bf16 v[24:27], v[164:167], v[196:199], v[24:27]
	v_mfma_f32_16x16x32_bf16 v[16:19], v[172:175], v[196:199], v[16:19]
	v_mfma_f32_16x16x32_bf16 v[8:11], v[164:167], v[226:229], v[8:11]
	v_mfma_f32_16x16x32_bf16 v[0:3], v[172:175], v[226:229], v[0:3]
	v_mfma_f32_16x16x32_bf16 v[56:59], v[168:171], v[184:187], v[56:59]
	v_mfma_f32_16x16x32_bf16 v[48:51], v[176:179], v[184:187], v[48:51]
	v_mfma_f32_16x16x32_bf16 v[40:43], v[168:171], v[192:195], v[40:43]
	v_mfma_f32_16x16x32_bf16 v[32:35], v[176:179], v[192:195], v[32:35]
	v_mfma_f32_16x16x32_bf16 v[24:27], v[168:171], v[222:225], v[24:27]
	v_mfma_f32_16x16x32_bf16 v[16:19], v[176:179], v[222:225], v[16:19]
	v_mfma_f32_16x16x32_bf16 v[8:11], v[168:171], v[230:233], v[8:11]
	v_mfma_f32_16x16x32_bf16 v[0:3], v[176:179], v[230:233], v[0:3]
	s_setprio 0
	s_barrier
; #define PG8_STAGE(bufoff, gbase, voff) do { _Pragma("unroll") for (int _i = 0; _i < 2; ++_i) \
;         __builtin_amdgcn_global_load_lds((const unsigned*)((const char*)(gbase) + (voff)[_i]), (PG8_LAS unsigned*)(lds + (bufoff) + ldsw + _i * 8192), 16, 0, 0); } while (0)
; #define PG8_LDA(dst, b, h) do { _Pragma("unroll") for (int m = 0; m < 4; ++m) _Pragma("unroll") for (int k = 0; k < 2; ++k) dst[m][k] = *(const PG8_LAS bf16x8*)(lds + PG8_SA(b, h) + aoff + m * 2048 + k * 1024); } while (0)
; #define PG8_LDB(dst, b, h) do { _Pragma("unroll") for (int n = 0; n < 2; ++n) _Pragma("unroll") for (int k = 0; k < 2; ++k) dst[n][k] = *(const PG8_LAS bf16x8*)(lds + PG8_SB(b, h) + boff + n * 2048 + k * 1024); } while (0)
; #define PG8_MMA(ai, bj, At, Bt) do { __builtin_amdgcn_s_setprio(1); _Pragma("unroll") for (int m = 0; m < 4; ++m) _Pragma("unroll") for (int n = 0; n < 2; ++n) _Pragma("unroll") for (int k = 0; k < 2; ++k) \
;         acc[ai][bj][m][n] = __builtin_amdgcn_mfma_f32_16x16x32_bf16(Bt[n][k], At[m][k], acc[ai][bj][m][n], 0, 0, 0); __builtin_amdgcn_s_setprio(0); } while (0)
; #define PG8_WAIT_V(n) asm volatile("s_waitcnt vmcnt(" #n ")" ::: "memory")
; #define PG8_WAIT_L(n) asm volatile("s_waitcnt lgkmcnt(" #n ")" ::: "memory")
; #define PG8_BAR __builtin_amdgcn_s_barrier()
; #define PG8_SCHED __builtin_amdgcn_sched_barrier(0)
; template <class Epi, class Sched, bool ALIGN_EPI = false, bool SP2 = false>
; __device__ __forceinline__ void gemm_phase(PG8_LAS unsigned char* lds, const Gemm g, const Sched& S, const Epi& E) {
;     ...
;             PG8_LDB(B0, 1, 0); PG8_LDB(B1, 1, 1); PG8_SCHED; PG8_LDA(At, 1, 0); PG8_STAGE(PG8_SA(0, 1), a2 + hstep, voffA);
;             PG8_WAIT_V(8); PG8_WAIT_L(0); PG8_BAR; PG8_MMA(0, 0, At, B0); PG8_MMA(0, 1, At, B1); PG8_BAR; PG8_SCHED;
;             PG8_LDA(At, 1, 1); PG8_STAGE(PG8_SB(1, 0), b3, voffB); PG8_STAGE(PG8_SB(1, 1), b3 + hstep, voffB); PG8_STAGE(PG8_SA(1, 0), a3, voffA);
;             PG8_WAIT_V(8); PG8_WAIT_L(0); PG8_BAR; PG8_MMA(1, 0, At, B0); PG8_MMA(1, 1, At, B1); PG8_BAR; PG8_SCHED;
;     ...
;         if constexpr (ALIGN_EPI) { if (wr == 0) PG8_BAR; }
	s_add_i32 s76, 0, 0x18000
	s_add_i32 s77, 0, 0x1c000
	ds_read_b128 v[144:147], v200 offset:32768
	ds_read_b128 v[148:151], v200 offset:33792
	ds_read_b128 v[152:155], v200 offset:34816
	ds_read_b128 v[156:159], v200 offset:35840
	ds_read_b128 v[164:167], v200 offset:49152
	ds_read_b128 v[168:171], v200 offset:50176
	ds_read_b128 v[172:175], v200 offset:51200
	ds_read_b128 v[176:179], v200 offset:52224
	s_add_u32 s52, s52, 0x80000
	s_addc_u32 s53, s53, 0
	s_mov_b32 m0, s56
	ds_read_b128 v[180:183], v143 offset:32768
	ds_read_b128 v[184:187], v143 offset:33792
	ds_read_b128 v[188:191], v143 offset:34816
	ds_read_b128 v[192:195], v143 offset:35840
	ds_read_b128 v[196:199], v143 offset:36864
	ds_read_b128 v[222:225], v143 offset:37888
	ds_read_b128 v[226:229], v143 offset:38912
	ds_read_b128 v[230:233], v143 offset:39936
	global_load_lds_dwordx4 v132, s[52:53]
	s_mov_b32 m0, s57
	s_nop 0
	global_load_lds_dwordx4 v130, s[52:53]
	s_waitcnt vmcnt(8)
	s_waitcnt lgkmcnt(0)
	s_barrier
	s_setprio 1
	s_waitcnt lgkmcnt(0)
	v_mfma_f32_16x16x32_bf16 v[124:127], v[144:147], v[180:183], v[124:127]
	v_mfma_f32_16x16x32_bf16 v[116:119], v[152:155], v[180:183], v[116:119]
	v_mfma_f32_16x16x32_bf16 v[108:111], v[144:147], v[188:191], v[108:111]
	v_mfma_f32_16x16x32_bf16 v[100:103], v[152:155], v[188:191], v[100:103]
	v_mfma_f32_16x16x32_bf16 v[92:95], v[144:147], v[196:199], v[92:95]
	v_mfma_f32_16x16x32_bf16 v[84:87], v[152:155], v[196:199], v[84:87]
	v_mfma_f32_16x16x32_bf16 v[76:79], v[144:147], v[226:229], v[76:79]
	v_mfma_f32_16x16x32_bf16 v[68:71], v[152:155], v[226:229], v[68:71]
	v_mfma_f32_16x16x32_bf16 v[124:127], v[148:151], v[184:187], v[124:127]
	v_mfma_f32_16x16x32_bf16 v[116:119], v[156:159], v[184:187], v[116:119]
	v_mfma_f32_16x16x32_bf16 v[108:111], v[148:151], v[192:195], v[108:111]
	v_mfma_f32_16x16x32_bf16 v[100:103], v[156:159], v[192:195], v[100:103]
	v_mfma_f32_16x16x32_bf16 v[92:95], v[148:151], v[222:225], v[92:95]
	v_mfma_f32_16x16x32_bf16 v[84:87], v[156:159], v[222:225], v[84:87]
	v_mfma_f32_16x16x32_bf16 v[76:79], v[148:151], v[230:233], v[76:79]
	v_mfma_f32_16x16x32_bf16 v[68:71], v[156:159], v[230:233], v[68:71]
	v_mfma_f32_16x16x32_bf16 v[120:123], v[164:167], v[180:183], v[120:123]
	v_mfma_f32_16x16x32_bf16 v[112:115], v[172:175], v[180:183], v[112:115]
	v_mfma_f32_16x16x32_bf16 v[104:107], v[164:167], v[188:191], v[104:107]
	v_mfma_f32_16x16x32_bf16 v[96:99], v[172:175], v[188:191], v[96:99]
	v_mfma_f32_16x16x32_bf16 v[88:91], v[164:167], v[196:199], v[88:91]
	v_mfma_f32_16x16x32_bf16 v[80:83], v[172:175], v[196:199], v[80:83]
	v_mfma_f32_16x16x32_bf16 v[72:75], v[164:167], v[226:229], v[72:75]
	v_mfma_f32_16x16x32_bf16 v[64:67], v[172:175], v[226:229], v[64:67]
	v_mfma_f32_16x16x32_bf16 v[120:123], v[168:171], v[184:187], v[120:123]
	v_mfma_f32_16x16x32_bf16 v[112:115], v[176:179], v[184:187], v[112:115]
	v_mfma_f32_16x16x32_bf16 v[104:107], v[168:171], v[192:195], v[104:107]
	v_mfma_f32_16x16x32_bf16 v[96:99], v[176:179], v[192:195], v[96:99]
	v_mfma_f32_16x16x32_bf16 v[88:91], v[168:171], v[222:225], v[88:91]
	v_mfma_f32_16x16x32_bf16 v[80:83], v[176:179], v[222:225], v[80:83]
	v_mfma_f32_16x16x32_bf16 v[72:75], v[168:171], v[230:233], v[72:75]
	v_mfma_f32_16x16x32_bf16 v[64:67], v[176:179], v[230:233], v[64:67]
	s_setprio 0
	s_barrier
	s_add_i32 s52, s76, s24
	s_mov_b32 m0, s52
	ds_read_b128 v[180:183], v143 offset:49152
	ds_read_b128 v[184:187], v143 offset:50176
	ds_read_b128 v[188:191], v143 offset:51200
	ds_read_b128 v[192:195], v143 offset:52224
	ds_read_b128 v[196:199], v143 offset:53248
	ds_read_b128 v[222:225], v143 offset:54272
	ds_read_b128 v[226:229], v143 offset:55296
	ds_read_b128 v[230:233], v143 offset:56320
	s_add_u32 s4, s4, 0x80
	s_addc_u32 s5, s5, 0
	global_load_lds_dwordx4 v160, s[4:5]
	s_add_i32 m0, s52, 0x2000
	s_add_i32 s52, s77, s24
	global_load_lds_dwordx4 v128, s[4:5]
	s_add_u32 s4, s4, 0x80000
	s_addc_u32 s5, s5, 0
	s_mov_b32 m0, s52
	s_nop 0
	global_load_lds_dwordx4 v160, s[4:5]
	s_add_i32 m0, s52, 0x2000
	s_nop 0
	global_load_lds_dwordx4 v128, s[4:5]
	s_mov_b32 m0, s58
	s_nop 0
	global_load_lds_dwordx4 v132, s[98:99]
	s_mov_b32 m0, s59
	s_nop 0
	global_load_lds_dwordx4 v130, s[98:99]
	s_waitcnt vmcnt(8)
	s_waitcnt lgkmcnt(0)
	s_barrier
	s_setprio 1
	s_waitcnt lgkmcnt(0)
	v_mfma_f32_16x16x32_bf16 v[60:63], v[144:147], v[180:183], v[60:63]
	v_mfma_f32_16x16x32_bf16 v[52:55], v[152:155], v[180:183], v[52:55]
	v_mfma_f32_16x16x32_bf16 v[44:47], v[144:147], v[188:191], v[44:47]
	v_mfma_f32_16x16x32_bf16 v[36:39], v[152:155], v[188:191], v[36:39]
	v_mfma_f32_16x16x32_bf16 v[28:31], v[144:147], v[196:199], v[28:31]
	v_mfma_f32_16x16x32_bf16 v[20:23], v[152:155], v[196:199], v[20:23]
	v_mfma_f32_16x16x32_bf16 v[12:15], v[144:147], v[226:229], v[12:15]
	v_mfma_f32_16x16x32_bf16 v[4:7], v[152:155], v[226:229], v[4:7]
	v_mfma_f32_16x16x32_bf16 v[60:63], v[148:151], v[184:187], v[60:63]
	v_mfma_f32_16x16x32_bf16 v[52:55], v[156:159], v[184:187], v[52:55]
	v_mfma_f32_16x16x32_bf16 v[44:47], v[148:151], v[192:195], v[44:47]
	v_mfma_f32_16x16x32_bf16 v[36:39], v[156:159], v[192:195], v[36:39]
	v_mfma_f32_16x16x32_bf16 v[28:31], v[148:151], v[222:225], v[28:31]
	v_mfma_f32_16x16x32_bf16 v[20:23], v[156:159], v[222:225], v[20:23]
	v_mfma_f32_16x16x32_bf16 v[12:15], v[148:151], v[230:233], v[12:15]
	v_mfma_f32_16x16x32_bf16 v[4:7], v[156:159], v[230:233], v[4:7]
	v_mfma_f32_16x16x32_bf16 v[56:59], v[164:167], v[180:183], v[56:59]
	v_mfma_f32_16x16x32_bf16 v[48:51], v[172:175], v[180:183], v[48:51]
	v_mfma_f32_16x16x32_bf16 v[40:43], v[164:167], v[188:191], v[40:43]
	v_mfma_f32_16x16x32_bf16 v[32:35], v[172:175], v[188:191], v[32:35]
	v_mfma_f32_16x16x32_bf16 v[24:27], v[164:167], v[196:199], v[24:27]
	v_mfma_f32_16x16x32_bf16 v[16:19], v[172:175], v[196:199], v[16:19]
	v_mfma_f32_16x16x32_bf16 v[8:11], v[164:167], v[226:229], v[8:11]
	v_mfma_f32_16x16x32_bf16 v[0:3], v[172:175], v[226:229], v[0:3]
	v_mfma_f32_16x16x32_bf16 v[56:59], v[168:171], v[184:187], v[56:59]
	v_mfma_f32_16x16x32_bf16 v[48:51], v[176:179], v[184:187], v[48:51]
	v_mfma_f32_16x16x32_bf16 v[40:43], v[168:171], v[192:195], v[40:43]
	v_mfma_f32_16x16x32_bf16 v[32:35], v[176:179], v[192:195], v[32:35]
	v_mfma_f32_16x16x32_bf16 v[24:27], v[168:171], v[222:225], v[24:27]
	v_mfma_f32_16x16x32_bf16 v[16:19], v[176:179], v[222:225], v[16:19]
	v_mfma_f32_16x16x32_bf16 v[8:11], v[168:171], v[230:233], v[8:11]
	v_mfma_f32_16x16x32_bf16 v[0:3], v[176:179], v[230:233], v[0:3]
	s_setprio 0
	s_barrier
	s_add_i32 s75, s75, 2
	s_add_u32 s70, s70, 0x100
	s_addc_u32 s71, s71, 0
	s_add_u32 s73, s73, 0x100
	s_addc_u32 s74, s74, 0
	s_cmp_gt_u32 s75, 29
	s_cbranch_scc0 .LBB0_849
	s_and_b64 vcc, exec, s[8:9]
	s_cbranch_vccz .LBB0_852
	s_barrier
